# SwiGLU epilogue setup and its 8 stat loads issued before the ALIGN_EPI barrier (leading half's load latency overlaps its barrier wait)
# speedup vs baseline: 1.0101x; 1.0012x over previous
; #define PG8_STAGE(bufoff, gbase, voff) do { _Pragma("unroll") for (int _i = 0; _i < 2; ++_i) \
;         __builtin_amdgcn_global_load_lds((const unsigned*)((const char*)(gbase) + (voff)[_i]), (PG8_LAS unsigned*)(lds + (bufoff) + ldsw + _i * 8192), 16, 0, 0); } while (0)
; #define PG8_LDA(dst, b, h) do { _Pragma("unroll") for (int m = 0; m < 4; ++m) _Pragma("unroll") for (int k = 0; k < 2; ++k) dst[m][k] = *(const PG8_LAS bf16x8*)(lds + PG8_SA(b, h) + aoff + m * 2048 + k * 1024); } while (0)
; #define PG8_LDB(dst, b, h) do { _Pragma("unroll") for (int n = 0; n < 2; ++n) _Pragma("unroll") for (int k = 0; k < 2; ++k) dst[n][k] = *(const PG8_LAS bf16x8*)(lds + PG8_SB(b, h) + boff + n * 2048 + k * 1024); } while (0)
; #define PG8_MMA(ai, bj, At, Bt) do { __builtin_amdgcn_s_setprio(1); _Pragma("unroll") for (int m = 0; m < 4; ++m) _Pragma("unroll") for (int n = 0; n < 2; ++n) _Pragma("unroll") for (int k = 0; k < 2; ++k) \
;         acc[ai][bj][m][n] = __builtin_amdgcn_mfma_f32_16x16x32_bf16(Bt[n][k], At[m][k], acc[ai][bj][m][n], 0, 0, 0); __builtin_amdgcn_s_setprio(0); } while (0)
; #define PG8_WAIT_V(n) asm volatile("s_waitcnt vmcnt(" #n ")" ::: "memory")
; #define PG8_WAIT_L(n) asm volatile("s_waitcnt lgkmcnt(" #n ")" ::: "memory")
; #define PG8_BAR __builtin_amdgcn_s_barrier()
; #define PG8_SCHED __builtin_amdgcn_sched_barrier(0)
; template <class Epi, class Sched, bool ALIGN_EPI = false, bool SP2 = false>
; __device__ __forceinline__ void gemm_phase(PG8_LAS unsigned char* lds, const Gemm g, const Sched& S, const Epi& E, const int tid) {
;     ...
;             PG8_LDB(B0, 0, 0); PG8_LDB(B1, 0, 1); PG8_SCHED; PG8_LDA(At, 0, 0); PG8_STAGE(PG8_SA(1, 1), a1 + hstepA, voffA);
;             PG8_WAIT_V(8); PG8_WAIT_L(0); PG8_BAR; PG8_MMA(0, 0, At, B0); PG8_MMA(0, 1, At, B1); PG8_BAR; PG8_SCHED;
;             PG8_LDA(At, 0, 1); PG8_STAGE(PG8_SB(0, 0), b2, voffB); PG8_STAGE(PG8_SB(0, 1), b2 + hstep, voffB); PG8_STAGE(PG8_SA(0, 0), a2, voffA);
;             PG8_WAIT_V(8); PG8_WAIT_L(0); PG8_BAR; PG8_MMA(1, 0, At, B0); PG8_MMA(1, 1, At, B1); PG8_BAR; PG8_SCHED;
.LBB0_279:
	ds_read_b128 v[144:147], v154
	ds_read_b128 v[148:151], v154 offset:1024
	ds_read_b128 v[160:163], v154 offset:2048
	ds_read_b128 v[164:167], v154 offset:3072
	ds_read_b128 v[168:171], v155
	ds_read_b128 v[172:175], v155 offset:1024
	ds_read_b128 v[176:179], v155 offset:2048
	ds_read_b128 v[180:183], v155 offset:3072
	s_add_u32 s26, s24, 0xfffc0080
	s_addc_u32 s27, s25, -1
	s_cmp_eq_u32 s58, 12
	s_cselect_b32 s29, s17, s27
	s_cselect_b32 s28, s54, s26
	s_cselect_b32 s27, s15, s57
	s_cselect_b32 s26, s55, s56
	v_lshl_add_u64 v[196:197], s[24:25], 0, v[136:137]
	s_add_i32 m0, s39, 0xc000
	ds_read_b128 v[184:187], v156
	ds_read_b128 v[188:191], v156 offset:1024
	ds_read_b128 v[192:195], v156 offset:2048
	ds_read_b128 v[200:203], v156 offset:3072
	ds_read_b128 v[204:207], v156 offset:4096
	ds_read_b128 v[208:211], v156 offset:5120
	ds_read_b128 v[212:215], v156 offset:6144
	ds_read_b128 v[216:219], v156 offset:7168
	global_load_lds_dwordx4 v[196:197], off
	v_lshl_add_u64 v[196:197], s[24:25], 0, v[138:139]
	s_add_i32 m0, s39, 0xe000
	s_nop 0
	global_load_lds_dwordx4 v[196:197], off
	s_waitcnt vmcnt(8)
	s_waitcnt lgkmcnt(0)
	s_barrier
	s_setprio 1
	s_waitcnt lgkmcnt(0)
	v_mfma_f32_16x16x32_bf16 v[124:127], v[144:147], v[184:187], v[124:127]
	v_mfma_f32_16x16x32_bf16 v[120:123], v[160:163], v[184:187], v[120:123]
	v_mfma_f32_16x16x32_bf16 v[108:111], v[144:147], v[192:195], v[108:111]
	v_mfma_f32_16x16x32_bf16 v[104:107], v[160:163], v[192:195], v[104:107]
	v_mfma_f32_16x16x32_bf16 v[92:95], v[144:147], v[204:207], v[92:95]
	v_mfma_f32_16x16x32_bf16 v[88:91], v[160:163], v[204:207], v[88:91]
	v_mfma_f32_16x16x32_bf16 v[76:79], v[144:147], v[212:215], v[76:79]
	v_mfma_f32_16x16x32_bf16 v[72:75], v[160:163], v[212:215], v[72:75]
	v_mfma_f32_16x16x32_bf16 v[124:127], v[148:151], v[188:191], v[124:127]
	v_mfma_f32_16x16x32_bf16 v[120:123], v[164:167], v[188:191], v[120:123]
	v_mfma_f32_16x16x32_bf16 v[108:111], v[148:151], v[200:203], v[108:111]
	v_mfma_f32_16x16x32_bf16 v[104:107], v[164:167], v[200:203], v[104:107]
	v_mfma_f32_16x16x32_bf16 v[92:95], v[148:151], v[208:211], v[92:95]
	v_mfma_f32_16x16x32_bf16 v[88:91], v[164:167], v[208:211], v[88:91]
	v_mfma_f32_16x16x32_bf16 v[76:79], v[148:151], v[216:219], v[76:79]
	v_mfma_f32_16x16x32_bf16 v[72:75], v[164:167], v[216:219], v[72:75]
	s_setprio 0
	s_setprio 1
	v_mfma_f32_16x16x32_bf16 v[116:119], v[168:171], v[184:187], v[116:119]
	v_mfma_f32_16x16x32_bf16 v[112:115], v[176:179], v[184:187], v[112:115]
	v_mfma_f32_16x16x32_bf16 v[100:103], v[168:171], v[192:195], v[100:103]
	v_mfma_f32_16x16x32_bf16 v[96:99], v[176:179], v[192:195], v[96:99]
	v_mfma_f32_16x16x32_bf16 v[84:87], v[168:171], v[204:207], v[84:87]
	v_mfma_f32_16x16x32_bf16 v[80:83], v[176:179], v[204:207], v[80:83]
	v_mfma_f32_16x16x32_bf16 v[68:71], v[168:171], v[212:215], v[68:71]
	v_mfma_f32_16x16x32_bf16 v[64:67], v[176:179], v[212:215], v[64:67]
	v_mfma_f32_16x16x32_bf16 v[116:119], v[172:175], v[188:191], v[116:119]
	v_mfma_f32_16x16x32_bf16 v[112:115], v[180:183], v[188:191], v[112:115]
	v_mfma_f32_16x16x32_bf16 v[100:103], v[172:175], v[200:203], v[100:103]
	v_mfma_f32_16x16x32_bf16 v[96:99], v[180:183], v[200:203], v[96:99]
	v_mfma_f32_16x16x32_bf16 v[84:87], v[172:175], v[208:211], v[84:87]
	v_mfma_f32_16x16x32_bf16 v[80:83], v[180:183], v[208:211], v[80:83]
	v_mfma_f32_16x16x32_bf16 v[68:71], v[172:175], v[216:219], v[68:71]
	v_mfma_f32_16x16x32_bf16 v[64:67], v[180:183], v[216:219], v[64:67]
	s_setprio 0
	s_barrier
	s_mov_b32 m0, s23
	v_lshl_add_u64 v[196:197], s[26:27], 0, v[132:133]
	s_add_u32 s60, s26, 0x40000
	ds_read_b128 v[184:187], v156 offset:16384
	ds_read_b128 v[188:191], v156 offset:17408
	ds_read_b128 v[192:195], v156 offset:18432
	ds_read_b128 v[200:203], v156 offset:19456
	ds_read_b128 v[204:207], v156 offset:20480
	ds_read_b128 v[208:211], v156 offset:21504
	ds_read_b128 v[212:215], v156 offset:22528
	ds_read_b128 v[216:219], v156 offset:23552
	global_load_lds_dwordx4 v[196:197], off
	v_lshl_add_u64 v[220:221], s[26:27], 0, v[128:129]
	s_mov_b32 m0, s36
	s_addc_u32 s61, s27, 0
	global_load_lds_dwordx4 v[220:221], off
	v_lshl_add_u64 v[222:223], s[60:61], 0, v[132:133]
	s_mov_b32 m0, s37
	v_lshl_add_u64 v[224:225], s[28:29], 0, v[130:131]
	global_load_lds_dwordx4 v[222:223], off
	v_lshl_add_u64 v[222:223], s[60:61], 0, v[128:129]
	s_mov_b32 m0, s38
	s_nop 0
	global_load_lds_dwordx4 v[222:223], off
	v_lshl_add_u64 v[222:223], s[28:29], 0, v[134:135]
	s_mov_b32 m0, s39
	s_nop 0
	global_load_lds_dwordx4 v[222:223], off
	s_mov_b32 m0, s40
	s_nop 0
	global_load_lds_dwordx4 v[224:225], off
	s_waitcnt vmcnt(8)
	s_waitcnt lgkmcnt(0)
	s_barrier
; #define PG8_STAGE(bufoff, gbase, voff) do { _Pragma("unroll") for (int _i = 0; _i < 2; ++_i) \
;         __builtin_amdgcn_global_load_lds((const unsigned*)((const char*)(gbase) + (voff)[_i]), (PG8_LAS unsigned*)(lds + (bufoff) + ldsw + _i * 8192), 16, 0, 0); } while (0)
; #define PG8_LDA(dst, b, h) do { _Pragma("unroll") for (int m = 0; m < 4; ++m) _Pragma("unroll") for (int k = 0; k < 2; ++k) dst[m][k] = *(const PG8_LAS bf16x8*)(lds + PG8_SA(b, h) + aoff + m * 2048 + k * 1024); } while (0)
; #define PG8_LDB(dst, b, h) do { _Pragma("unroll") for (int n = 0; n < 2; ++n) _Pragma("unroll") for (int k = 0; k < 2; ++k) dst[n][k] = *(const PG8_LAS bf16x8*)(lds + PG8_SB(b, h) + boff + n * 2048 + k * 1024); } while (0)
; #define PG8_MMA(ai, bj, At, Bt) do { __builtin_amdgcn_s_setprio(1); _Pragma("unroll") for (int m = 0; m < 4; ++m) _Pragma("unroll") for (int n = 0; n < 2; ++n) _Pragma("unroll") for (int k = 0; k < 2; ++k) \
;         acc[ai][bj][m][n] = __builtin_amdgcn_mfma_f32_16x16x32_bf16(Bt[n][k], At[m][k], acc[ai][bj][m][n], 0, 0, 0); __builtin_amdgcn_s_setprio(0); } while (0)
; #define PG8_WAIT_V(n) asm volatile("s_waitcnt vmcnt(" #n ")" ::: "memory")
; #define PG8_WAIT_L(n) asm volatile("s_waitcnt lgkmcnt(" #n ")" ::: "memory")
; #define PG8_BAR __builtin_amdgcn_s_barrier()
; #define PG8_SCHED __builtin_amdgcn_sched_barrier(0)
; template <class Epi, class Sched, bool ALIGN_EPI = false, bool SP2 = false>
; __device__ __forceinline__ void gemm_phase(PG8_LAS unsigned char* lds, const Gemm g, const Sched& S, const Epi& E, const int tid) {
;     ...
;             PG8_WAIT_V(8); PG8_WAIT_L(0); PG8_BAR; PG8_MMA(1, 0, At, B0); PG8_MMA(1, 1, At, B1); PG8_BAR; PG8_SCHED;
;             PG8_LDB(B0, 1, 0); PG8_LDB(B1, 1, 1); PG8_SCHED; PG8_LDA(At, 1, 0); PG8_STAGE(PG8_SA(0, 1), a2 + hstepA, voffA);
;             PG8_WAIT_V(8); PG8_WAIT_L(0); PG8_BAR; PG8_MMA(0, 0, At, B0); PG8_MMA(0, 1, At, B1); PG8_BAR; PG8_SCHED;
	s_setprio 1
	s_waitcnt lgkmcnt(0)
	v_mfma_f32_16x16x32_bf16 v[60:63], v[144:147], v[184:187], v[60:63]
	v_mfma_f32_16x16x32_bf16 v[56:59], v[160:163], v[184:187], v[56:59]
	v_mfma_f32_16x16x32_bf16 v[44:47], v[144:147], v[192:195], v[44:47]
	v_mfma_f32_16x16x32_bf16 v[40:43], v[160:163], v[192:195], v[40:43]
	v_mfma_f32_16x16x32_bf16 v[28:31], v[144:147], v[204:207], v[28:31]
	v_mfma_f32_16x16x32_bf16 v[24:27], v[160:163], v[204:207], v[24:27]
	v_mfma_f32_16x16x32_bf16 v[12:15], v[144:147], v[212:215], v[12:15]
	v_mfma_f32_16x16x32_bf16 v[8:11], v[160:163], v[212:215], v[8:11]
	v_mfma_f32_16x16x32_bf16 v[60:63], v[148:151], v[188:191], v[60:63]
	v_mfma_f32_16x16x32_bf16 v[56:59], v[164:167], v[188:191], v[56:59]
	v_mfma_f32_16x16x32_bf16 v[44:47], v[148:151], v[200:203], v[44:47]
	v_mfma_f32_16x16x32_bf16 v[40:43], v[164:167], v[200:203], v[40:43]
	v_mfma_f32_16x16x32_bf16 v[28:31], v[148:151], v[208:211], v[28:31]
	v_mfma_f32_16x16x32_bf16 v[24:27], v[164:167], v[208:211], v[24:27]
	v_mfma_f32_16x16x32_bf16 v[12:15], v[148:151], v[216:219], v[12:15]
	v_mfma_f32_16x16x32_bf16 v[8:11], v[164:167], v[216:219], v[8:11]
	s_setprio 0
	s_setprio 1
	v_mfma_f32_16x16x32_bf16 v[52:55], v[168:171], v[184:187], v[52:55]
	v_mfma_f32_16x16x32_bf16 v[48:51], v[176:179], v[184:187], v[48:51]
	v_mfma_f32_16x16x32_bf16 v[36:39], v[168:171], v[192:195], v[36:39]
	v_mfma_f32_16x16x32_bf16 v[32:35], v[176:179], v[192:195], v[32:35]
	v_mfma_f32_16x16x32_bf16 v[20:23], v[168:171], v[204:207], v[20:23]
	v_mfma_f32_16x16x32_bf16 v[16:19], v[176:179], v[204:207], v[16:19]
	v_mfma_f32_16x16x32_bf16 v[4:7], v[168:171], v[212:215], v[4:7]
	v_mfma_f32_16x16x32_bf16 v[0:3], v[176:179], v[212:215], v[0:3]
	v_mfma_f32_16x16x32_bf16 v[52:55], v[172:175], v[188:191], v[52:55]
	v_mfma_f32_16x16x32_bf16 v[48:51], v[180:183], v[188:191], v[48:51]
	v_mfma_f32_16x16x32_bf16 v[36:39], v[172:175], v[200:203], v[36:39]
	v_mfma_f32_16x16x32_bf16 v[32:35], v[180:183], v[200:203], v[32:35]
	v_mfma_f32_16x16x32_bf16 v[20:23], v[172:175], v[208:211], v[20:23]
	v_mfma_f32_16x16x32_bf16 v[16:19], v[180:183], v[208:211], v[16:19]
	v_mfma_f32_16x16x32_bf16 v[4:7], v[172:175], v[216:219], v[4:7]
	v_mfma_f32_16x16x32_bf16 v[0:3], v[180:183], v[216:219], v[0:3]
	s_setprio 0
	s_barrier
	ds_read_b128 v[144:147], v157
	ds_read_b128 v[148:151], v157 offset:1024
	ds_read_b128 v[160:163], v157 offset:2048
	ds_read_b128 v[164:167], v157 offset:3072
	ds_read_b128 v[168:171], v158
	ds_read_b128 v[172:175], v158 offset:1024
	ds_read_b128 v[176:179], v158 offset:2048
	ds_read_b128 v[180:183], v158 offset:3072
	s_add_u32 s28, s28, 0x40000
	s_addc_u32 s29, s29, 0
	s_mov_b32 m0, s41
	v_lshl_add_u64 v[226:227], s[28:29], 0, v[134:135]
	ds_read_b128 v[184:187], v156 offset:32768
	ds_read_b128 v[188:191], v156 offset:33792
	ds_read_b128 v[192:195], v156 offset:34816
	ds_read_b128 v[200:203], v156 offset:35840
	ds_read_b128 v[204:207], v156 offset:36864
	ds_read_b128 v[208:211], v156 offset:37888
	ds_read_b128 v[212:215], v156 offset:38912
	ds_read_b128 v[216:219], v156 offset:39936
	global_load_lds_dwordx4 v[226:227], off
	v_lshl_add_u64 v[226:227], s[28:29], 0, v[130:131]
	s_mov_b32 m0, s42
	s_nop 0
	global_load_lds_dwordx4 v[226:227], off
	s_waitcnt vmcnt(8)
	s_waitcnt lgkmcnt(0)
	s_barrier
	s_setprio 1
	s_waitcnt lgkmcnt(0)
	v_mfma_f32_16x16x32_bf16 v[124:127], v[144:147], v[184:187], v[124:127]
	v_mfma_f32_16x16x32_bf16 v[120:123], v[160:163], v[184:187], v[120:123]
	v_mfma_f32_16x16x32_bf16 v[108:111], v[144:147], v[192:195], v[108:111]
	v_mfma_f32_16x16x32_bf16 v[104:107], v[160:163], v[192:195], v[104:107]
	v_mfma_f32_16x16x32_bf16 v[92:95], v[144:147], v[204:207], v[92:95]
	v_mfma_f32_16x16x32_bf16 v[88:91], v[160:163], v[204:207], v[88:91]
	v_mfma_f32_16x16x32_bf16 v[76:79], v[144:147], v[212:215], v[76:79]
	v_mfma_f32_16x16x32_bf16 v[72:75], v[160:163], v[212:215], v[72:75]
	v_mfma_f32_16x16x32_bf16 v[124:127], v[148:151], v[188:191], v[124:127]
	v_mfma_f32_16x16x32_bf16 v[120:123], v[164:167], v[188:191], v[120:123]
	v_mfma_f32_16x16x32_bf16 v[108:111], v[148:151], v[200:203], v[108:111]
	v_mfma_f32_16x16x32_bf16 v[104:107], v[164:167], v[200:203], v[104:107]
	v_mfma_f32_16x16x32_bf16 v[92:95], v[148:151], v[208:211], v[92:95]
	v_mfma_f32_16x16x32_bf16 v[88:91], v[164:167], v[208:211], v[88:91]
	v_mfma_f32_16x16x32_bf16 v[76:79], v[148:151], v[216:219], v[76:79]
	v_mfma_f32_16x16x32_bf16 v[72:75], v[164:167], v[216:219], v[72:75]
	s_setprio 0
	s_setprio 1
	v_mfma_f32_16x16x32_bf16 v[116:119], v[168:171], v[184:187], v[116:119]
	v_mfma_f32_16x16x32_bf16 v[112:115], v[176:179], v[184:187], v[112:115]
	v_mfma_f32_16x16x32_bf16 v[100:103], v[168:171], v[192:195], v[100:103]
	v_mfma_f32_16x16x32_bf16 v[96:99], v[176:179], v[192:195], v[96:99]
	v_mfma_f32_16x16x32_bf16 v[84:87], v[168:171], v[204:207], v[84:87]
	v_mfma_f32_16x16x32_bf16 v[80:83], v[176:179], v[204:207], v[80:83]
	v_mfma_f32_16x16x32_bf16 v[68:71], v[168:171], v[212:215], v[68:71]
	v_mfma_f32_16x16x32_bf16 v[64:67], v[176:179], v[212:215], v[64:67]
	v_mfma_f32_16x16x32_bf16 v[116:119], v[172:175], v[188:191], v[116:119]
	v_mfma_f32_16x16x32_bf16 v[112:115], v[180:183], v[188:191], v[112:115]
	v_mfma_f32_16x16x32_bf16 v[100:103], v[172:175], v[200:203], v[100:103]
	v_mfma_f32_16x16x32_bf16 v[96:99], v[180:183], v[200:203], v[96:99]
	v_mfma_f32_16x16x32_bf16 v[84:87], v[172:175], v[208:211], v[84:87]
	v_mfma_f32_16x16x32_bf16 v[80:83], v[180:183], v[208:211], v[80:83]
	v_mfma_f32_16x16x32_bf16 v[68:71], v[172:175], v[216:219], v[68:71]
	v_mfma_f32_16x16x32_bf16 v[64:67], v[180:183], v[216:219], v[64:67]
	s_setprio 0
	s_barrier
; #define PG8_STAGE(bufoff, gbase, voff) do { _Pragma("unroll") for (int _i = 0; _i < 2; ++_i) \
;         __builtin_amdgcn_global_load_lds((const unsigned*)((const char*)(gbase) + (voff)[_i]), (PG8_LAS unsigned*)(lds + (bufoff) + ldsw + _i * 8192), 16, 0, 0); } while (0)
; #define PG8_LDA(dst, b, h) do { _Pragma("unroll") for (int m = 0; m < 4; ++m) _Pragma("unroll") for (int k = 0; k < 2; ++k) dst[m][k] = *(const PG8_LAS bf16x8*)(lds + PG8_SA(b, h) + aoff + m * 2048 + k * 1024); } while (0)
; #define PG8_MMA(ai, bj, At, Bt) do { __builtin_amdgcn_s_setprio(1); _Pragma("unroll") for (int m = 0; m < 4; ++m) _Pragma("unroll") for (int n = 0; n < 2; ++n) _Pragma("unroll") for (int k = 0; k < 2; ++k) \
;         acc[ai][bj][m][n] = __builtin_amdgcn_mfma_f32_16x16x32_bf16(Bt[n][k], At[m][k], acc[ai][bj][m][n], 0, 0, 0); __builtin_amdgcn_s_setprio(0); } while (0)
; #define PG8_WAIT_V(n) asm volatile("s_waitcnt vmcnt(" #n ")" ::: "memory")
; #define PG8_WAIT_L(n) asm volatile("s_waitcnt lgkmcnt(" #n ")" ::: "memory")
; #define PG8_BAR __builtin_amdgcn_s_barrier()
; #define PG8_SCHED __builtin_amdgcn_sched_barrier(0)
; template <class Epi, class Sched, bool ALIGN_EPI = false, bool SP2 = false>
; __device__ __forceinline__ void gemm_phase(PG8_LAS unsigned char* lds, const Gemm g, const Sched& S, const Epi& E, const int tid) {
;     ...
;             PG8_LDA(At, 1, 1); PG8_STAGE(PG8_SB(1, 0), b3, voffB); PG8_STAGE(PG8_SB(1, 1), b3 + hstep, voffB); PG8_STAGE(PG8_SA(1, 0), a3, voffA);
;             PG8_WAIT_V(8); PG8_WAIT_L(0); PG8_BAR; PG8_MMA(1, 0, At, B0); PG8_MMA(1, 1, At, B1); PG8_BAR; PG8_SCHED;
;     ...
;         if constexpr (ALIGN_EPI) { if (wr == 0) PG8_BAR; }
;         if constexpr (!Epi::AFTER_DRAIN) { E(acc, cur, wr, wc, fr, fq); S.done(cur); }
	s_mov_b32 m0, s45
	v_lshl_add_u64 v[196:197], v[196:197], 0, s[10:11]
	s_add_u32 s26, s26, 0x40080
	ds_read_b128 v[184:187], v156 offset:49152
	ds_read_b128 v[188:191], v156 offset:50176
	ds_read_b128 v[192:195], v156 offset:51200
	ds_read_b128 v[200:203], v156 offset:52224
	ds_read_b128 v[204:207], v156 offset:53248
	ds_read_b128 v[208:211], v156 offset:54272
	ds_read_b128 v[212:215], v156 offset:55296
	ds_read_b128 v[216:219], v156 offset:56320
	global_load_lds_dwordx4 v[196:197], off
	v_lshl_add_u64 v[196:197], v[220:221], 0, s[10:11]
	s_mov_b32 m0, s46
	s_addc_u32 s27, s27, 0
	global_load_lds_dwordx4 v[196:197], off
	v_lshl_add_u64 v[196:197], s[26:27], 0, v[132:133]
	s_mov_b32 m0, s49
	s_nop 0
	global_load_lds_dwordx4 v[196:197], off
	v_lshl_add_u64 v[196:197], s[26:27], 0, v[128:129]
	s_mov_b32 m0, s50
	s_nop 0
	global_load_lds_dwordx4 v[196:197], off
	v_lshl_add_u64 v[196:197], v[222:223], 0, s[10:11]
	s_mov_b32 m0, s47
	s_nop 0
	global_load_lds_dwordx4 v[196:197], off
	v_lshl_add_u64 v[196:197], v[224:225], 0, s[10:11]
	s_mov_b32 m0, s48
	s_nop 0
	global_load_lds_dwordx4 v[196:197], off
	s_waitcnt vmcnt(8)
	s_waitcnt lgkmcnt(0)
	s_barrier
	s_setprio 1
	s_waitcnt lgkmcnt(0)
	v_mfma_f32_16x16x32_bf16 v[60:63], v[144:147], v[184:187], v[60:63]
	v_mfma_f32_16x16x32_bf16 v[56:59], v[160:163], v[184:187], v[56:59]
	v_mfma_f32_16x16x32_bf16 v[44:47], v[144:147], v[192:195], v[44:47]
	v_mfma_f32_16x16x32_bf16 v[40:43], v[160:163], v[192:195], v[40:43]
	v_mfma_f32_16x16x32_bf16 v[28:31], v[144:147], v[204:207], v[28:31]
	v_mfma_f32_16x16x32_bf16 v[24:27], v[160:163], v[204:207], v[24:27]
	v_mfma_f32_16x16x32_bf16 v[12:15], v[144:147], v[212:215], v[12:15]
	v_mfma_f32_16x16x32_bf16 v[8:11], v[160:163], v[212:215], v[8:11]
	v_mfma_f32_16x16x32_bf16 v[60:63], v[148:151], v[188:191], v[60:63]
	v_mfma_f32_16x16x32_bf16 v[56:59], v[164:167], v[188:191], v[56:59]
	v_mfma_f32_16x16x32_bf16 v[44:47], v[148:151], v[200:203], v[44:47]
	v_mfma_f32_16x16x32_bf16 v[40:43], v[164:167], v[200:203], v[40:43]
	v_mfma_f32_16x16x32_bf16 v[28:31], v[148:151], v[208:211], v[28:31]
	v_mfma_f32_16x16x32_bf16 v[24:27], v[164:167], v[208:211], v[24:27]
	v_mfma_f32_16x16x32_bf16 v[12:15], v[148:151], v[216:219], v[12:15]
	v_mfma_f32_16x16x32_bf16 v[8:11], v[164:167], v[216:219], v[8:11]
	s_setprio 0
	s_setprio 1
	v_mfma_f32_16x16x32_bf16 v[52:55], v[168:171], v[184:187], v[52:55]
	v_mfma_f32_16x16x32_bf16 v[48:51], v[176:179], v[184:187], v[48:51]
	v_mfma_f32_16x16x32_bf16 v[36:39], v[168:171], v[192:195], v[36:39]
	v_mfma_f32_16x16x32_bf16 v[32:35], v[176:179], v[192:195], v[32:35]
	v_mfma_f32_16x16x32_bf16 v[20:23], v[168:171], v[204:207], v[20:23]
	v_mfma_f32_16x16x32_bf16 v[16:19], v[176:179], v[204:207], v[16:19]
	v_mfma_f32_16x16x32_bf16 v[4:7], v[168:171], v[212:215], v[4:7]
	v_mfma_f32_16x16x32_bf16 v[0:3], v[176:179], v[212:215], v[0:3]
	v_mfma_f32_16x16x32_bf16 v[52:55], v[172:175], v[188:191], v[52:55]
	v_mfma_f32_16x16x32_bf16 v[48:51], v[180:183], v[188:191], v[48:51]
	v_mfma_f32_16x16x32_bf16 v[36:39], v[172:175], v[200:203], v[36:39]
	v_mfma_f32_16x16x32_bf16 v[32:35], v[180:183], v[200:203], v[32:35]
	v_mfma_f32_16x16x32_bf16 v[20:23], v[172:175], v[208:211], v[20:23]
	v_mfma_f32_16x16x32_bf16 v[16:19], v[180:183], v[208:211], v[16:19]
	v_mfma_f32_16x16x32_bf16 v[4:7], v[172:175], v[216:219], v[4:7]
	v_mfma_f32_16x16x32_bf16 v[0:3], v[180:183], v[216:219], v[0:3]
	s_setprio 0
	s_barrier
	s_add_i32 s58, s58, 2
	s_add_u32 s24, s24, 0x100
	s_addc_u32 s25, s25, 0
	s_add_u32 s56, s56, 0x100
	s_addc_u32 s57, s57, 0
	s_cmp_gt_u32 s58, 13
	s_cbranch_scc0 .LBB0_279
	v_lshl_add_u32 v144, s22, 8, v152
	v_mov_b32_e32 v145, 0
	v_lshl_add_u64 v[150:151], v[144:145], 3, s[6:7]
	global_load_dwordx2 v[176:177], v[150:151], off
	global_load_dwordx2 v[178:179], v[150:151], off offset:128
	global_load_dwordx2 v[180:181], v[150:151], off offset:256
	global_load_dwordx2 v[182:183], v[150:151], off offset:384
	global_load_dwordx2 v[184:185], v[150:151], off offset:1024
	global_load_dwordx2 v[186:187], v[150:151], off offset:1152
	global_load_dwordx2 v[188:189], v[150:151], off offset:1280
	global_load_dwordx2 v[190:191], v[150:151], off offset:1408
	v_lshl_or_b32 v148, s53, 7, v153
	v_mul_u32_u24_e32 v146, s52, v144
	v_lshl_add_u32 v146, v148, 1, v146
	v_mov_b32_e32 v147, 0
	v_lshl_add_u64 v[146:147], v[146:147], 0, s[8:9]
	v_mov_b32_e32 v164, 1.0
	v_mov_b32_e32 v165, 1.0
	s_mov_b32 s101, 0
	s_and_b64 vcc, exec, s[12:13]
	s_cbranch_vccz .LBB0_282
	s_barrier
; __device__ __forceinline__ float ss_scale(const u64* ss, int row) { return __builtin_amdgcn_rsqf((float)ss[row] * (1.f / 4294967296.f / 1024.f) + EPS); }
; __device__ __forceinline__ unsigned pkbf(float lo, float hi) { typedef __bf16 bf2_t __attribute__((ext_vector_type(2))); f32x2 v = {lo, hi}; bf2_t b = __builtin_convertvector(v, bf2_t); return __builtin_bit_cast(unsigned, b); }
; __device__ __forceinline__ float silu_f(float g) { return g * __builtin_amdgcn_rcpf(1.f + __builtin_amdgcn_exp2f(-g * LOG2E)); }
;     __device__ __forceinline__ void operator()(const f32x4 (&acc)[2][2][4][2], const pg8::Unit& u, int wr, int wc, int fr, int fq) const {
;     ...
;             for (int m = 0; m < 4; ++m) {
;                 const int row = row0 + ai * 128 + m * 16;
;                 float s = ss_scale(ss, row);
;                 if constexpr (NN) s *= __builtin_amdgcn_rsqf(s * s * (float)ssw[row] * (1.f / 4294967296.f / 1024.f) + EPS);
;                 float a[8];
; #pragma unroll
;                 for (int n = 0; n < 2; ++n)
; #pragma unroll
;                     for (int i = 0; i < 4; ++i) { const float g = acc[ai][0][m][n][i] * s, uu = acc[ai][1][m][n][i] * s; a[4 * n + i] = silu_f(g) * uu; }
;                 u32x4 w; w.x = pkbf(a[0], a[1]); w.y = pkbf(a[2], a[3]); w.z = pkbf(a[4], a[5]); w.w = pkbf(a[6], a[7]);
;                 *(u32x4*)(O + (size_t)row * FF + col0) = w;
.LBB0_282:
	s_andn2_b64 vcc, exec, s[2:3]
	s_mov_b64 s[2:3], -1
	s_waitcnt vmcnt(7)
	v_cvt_f32_u32_e32 v166, v177
	v_cvt_f32_u32_e32 v167, v176
	v_fmamk_f32 v166, v166, 0x4f800000, v167
	v_fmamk_f32 v166, v166, 0x2a800000, v159
	v_rsq_f32_e32 v166, v166
	s_nop 0
	v_mul_f32_e32 v160, 0xbfb8aa3b, v166
	v_mul_f32_e32 v162, v166, v166
	v_pk_mul_f32 v[168:169], v[124:125], v[160:161] op_sel_hi:[1,0]
	v_pk_mul_f32 v[170:171], v[126:127], v[160:161] op_sel_hi:[1,0]
	v_pk_mul_f32 v[172:173], v[120:121], v[160:161] op_sel_hi:[1,0]
	v_pk_mul_f32 v[174:175], v[122:123], v[160:161] op_sel_hi:[1,0]
	v_exp_f32_e32 v168, v168
	v_exp_f32_e32 v169, v169
	v_exp_f32_e32 v170, v170
	v_exp_f32_e32 v171, v171
	v_exp_f32_e32 v172, v172
	v_exp_f32_e32 v173, v173
	v_exp_f32_e32 v174, v174
	v_exp_f32_e32 v175, v175
	v_pk_add_f32 v[168:169], v[168:169], v[164:165]
	v_pk_add_f32 v[170:171], v[170:171], v[164:165]
	v_pk_add_f32 v[172:173], v[172:173], v[164:165]
	v_pk_add_f32 v[174:175], v[174:175], v[164:165]
	v_rcp_f32_e32 v168, v168
	v_rcp_f32_e32 v169, v169
	v_rcp_f32_e32 v170, v170
	v_rcp_f32_e32 v171, v171
	v_rcp_f32_e32 v172, v172
	v_rcp_f32_e32 v173, v173
	v_rcp_f32_e32 v174, v174
	v_rcp_f32_e32 v175, v175
	v_pk_mul_f32 v[124:125], v[124:125], v[116:117]
	v_pk_mul_f32 v[126:127], v[126:127], v[118:119]
	v_pk_mul_f32 v[120:121], v[120:121], v[112:113]
	v_pk_mul_f32 v[122:123], v[122:123], v[114:115]
	v_pk_mul_f32 v[124:125], v[124:125], v[168:169]
	v_pk_mul_f32 v[126:127], v[126:127], v[170:171]
	v_pk_mul_f32 v[120:121], v[120:121], v[172:173]
	v_pk_mul_f32 v[122:123], v[122:123], v[174:175]
	v_pk_mul_f32 v[124:125], v[124:125], v[162:163] op_sel_hi:[1,0]
	v_pk_mul_f32 v[126:127], v[126:127], v[162:163] op_sel_hi:[1,0]
	v_pk_mul_f32 v[120:121], v[120:121], v[162:163] op_sel_hi:[1,0]
	v_pk_mul_f32 v[122:123], v[122:123], v[162:163] op_sel_hi:[1,0]
	v_cvt_pk_bf16_f32 v116, v124, v125
	v_cvt_pk_bf16_f32 v117, v126, v127
	v_cvt_pk_bf16_f32 v118, v120, v121
	v_cvt_pk_bf16_f32 v119, v122, v123
	global_store_dwordx4 v[146:147], v[116:119], off
	s_waitcnt vmcnt(7)
	v_cvt_f32_u32_e32 v166, v179
	v_cvt_f32_u32_e32 v167, v178
	v_fmamk_f32 v166, v166, 0x4f800000, v167
	v_fmamk_f32 v166, v166, 0x2a800000, v159
	v_rsq_f32_e32 v166, v166
	s_nop 0
	v_mul_f32_e32 v160, 0xbfb8aa3b, v166
	v_mul_f32_e32 v162, v166, v166
	v_pk_mul_f32 v[168:169], v[108:109], v[160:161] op_sel_hi:[1,0]
	v_pk_mul_f32 v[170:171], v[110:111], v[160:161] op_sel_hi:[1,0]
	v_pk_mul_f32 v[172:173], v[104:105], v[160:161] op_sel_hi:[1,0]
	v_pk_mul_f32 v[174:175], v[106:107], v[160:161] op_sel_hi:[1,0]
	v_exp_f32_e32 v168, v168
	v_exp_f32_e32 v169, v169
	v_exp_f32_e32 v170, v170
	v_exp_f32_e32 v171, v171
	v_exp_f32_e32 v172, v172
	v_exp_f32_e32 v173, v173
	v_exp_f32_e32 v174, v174
	v_exp_f32_e32 v175, v175
	v_pk_add_f32 v[168:169], v[168:169], v[164:165]
	v_pk_add_f32 v[170:171], v[170:171], v[164:165]
	v_pk_add_f32 v[172:173], v[172:173], v[164:165]
	v_pk_add_f32 v[174:175], v[174:175], v[164:165]
	v_rcp_f32_e32 v168, v168
	v_rcp_f32_e32 v169, v169
	v_rcp_f32_e32 v170, v170
	v_rcp_f32_e32 v171, v171
	v_rcp_f32_e32 v172, v172
	v_rcp_f32_e32 v173, v173
	v_rcp_f32_e32 v174, v174
	v_rcp_f32_e32 v175, v175
	v_pk_mul_f32 v[108:109], v[108:109], v[100:101]
	v_pk_mul_f32 v[110:111], v[110:111], v[102:103]
	v_pk_mul_f32 v[104:105], v[104:105], v[96:97]
	v_pk_mul_f32 v[106:107], v[106:107], v[98:99]
	v_pk_mul_f32 v[108:109], v[108:109], v[168:169]
	v_pk_mul_f32 v[110:111], v[110:111], v[170:171]
	v_pk_mul_f32 v[104:105], v[104:105], v[172:173]
	v_pk_mul_f32 v[106:107], v[106:107], v[174:175]
	v_pk_mul_f32 v[108:109], v[108:109], v[162:163] op_sel_hi:[1,0]
	v_pk_mul_f32 v[110:111], v[110:111], v[162:163] op_sel_hi:[1,0]
	v_pk_mul_f32 v[104:105], v[104:105], v[162:163] op_sel_hi:[1,0]
	v_pk_mul_f32 v[106:107], v[106:107], v[162:163] op_sel_hi:[1,0]
	v_cvt_pk_bf16_f32 v100, v108, v109
	v_cvt_pk_bf16_f32 v101, v110, v111
	v_cvt_pk_bf16_f32 v102, v104, v105
	v_cvt_pk_bf16_f32 v103, v106, v107
	s_mov_b32 s100, 0x16000
	v_lshl_add_u64 v[148:149], v[146:147], 0, s[100:101]
	global_store_dwordx4 v[148:149], v[100:103], off
	s_waitcnt vmcnt(7)
	v_cvt_f32_u32_e32 v166, v181
	v_cvt_f32_u32_e32 v167, v180
	v_fmamk_f32 v166, v166, 0x4f800000, v167
	v_fmamk_f32 v166, v166, 0x2a800000, v159
	v_rsq_f32_e32 v166, v166
	s_nop 0
	v_mul_f32_e32 v160, 0xbfb8aa3b, v166
	v_mul_f32_e32 v162, v166, v166
	v_pk_mul_f32 v[168:169], v[92:93], v[160:161] op_sel_hi:[1,0]
	v_pk_mul_f32 v[170:171], v[94:95], v[160:161] op_sel_hi:[1,0]
	v_pk_mul_f32 v[172:173], v[88:89], v[160:161] op_sel_hi:[1,0]
	v_pk_mul_f32 v[174:175], v[90:91], v[160:161] op_sel_hi:[1,0]
	v_exp_f32_e32 v168, v168
	v_exp_f32_e32 v169, v169
	v_exp_f32_e32 v170, v170
	v_exp_f32_e32 v171, v171
	v_exp_f32_e32 v172, v172
	v_exp_f32_e32 v173, v173
	v_exp_f32_e32 v174, v174
	v_exp_f32_e32 v175, v175
	v_pk_add_f32 v[168:169], v[168:169], v[164:165]
	v_pk_add_f32 v[170:171], v[170:171], v[164:165]
	v_pk_add_f32 v[172:173], v[172:173], v[164:165]
	v_pk_add_f32 v[174:175], v[174:175], v[164:165]
	v_rcp_f32_e32 v168, v168
	v_rcp_f32_e32 v169, v169
	v_rcp_f32_e32 v170, v170
	v_rcp_f32_e32 v171, v171
	v_rcp_f32_e32 v172, v172
	v_rcp_f32_e32 v173, v173
	v_rcp_f32_e32 v174, v174
	v_rcp_f32_e32 v175, v175
	v_pk_mul_f32 v[92:93], v[92:93], v[84:85]
	v_pk_mul_f32 v[94:95], v[94:95], v[86:87]
	v_pk_mul_f32 v[88:89], v[88:89], v[80:81]
	v_pk_mul_f32 v[90:91], v[90:91], v[82:83]
	v_pk_mul_f32 v[92:93], v[92:93], v[168:169]
	v_pk_mul_f32 v[94:95], v[94:95], v[170:171]
	v_pk_mul_f32 v[88:89], v[88:89], v[172:173]
	v_pk_mul_f32 v[90:91], v[90:91], v[174:175]
	v_pk_mul_f32 v[92:93], v[92:93], v[162:163] op_sel_hi:[1,0]
	v_pk_mul_f32 v[94:95], v[94:95], v[162:163] op_sel_hi:[1,0]
	v_pk_mul_f32 v[88:89], v[88:89], v[162:163] op_sel_hi:[1,0]
	v_pk_mul_f32 v[90:91], v[90:91], v[162:163] op_sel_hi:[1,0]
	v_cvt_pk_bf16_f32 v84, v92, v93
	v_cvt_pk_bf16_f32 v85, v94, v95
	v_cvt_pk_bf16_f32 v86, v88, v89
	v_cvt_pk_bf16_f32 v87, v90, v91
	s_mov_b32 s100, 0x2c000
	v_lshl_add_u64 v[148:149], v[146:147], 0, s[100:101]
	global_store_dwordx4 v[148:149], v[84:87], off
	s_waitcnt vmcnt(7)
; __device__ __forceinline__ float ss_scale(const u64* ss, int row) { return __builtin_amdgcn_rsqf((float)ss[row] * (1.f / 4294967296.f / 1024.f) + EPS); }
; __device__ __forceinline__ unsigned pkbf(float lo, float hi) { typedef __bf16 bf2_t __attribute__((ext_vector_type(2))); f32x2 v = {lo, hi}; bf2_t b = __builtin_convertvector(v, bf2_t); return __builtin_bit_cast(unsigned, b); }
; __device__ __forceinline__ float silu_f(float g) { return g * __builtin_amdgcn_rcpf(1.f + __builtin_amdgcn_exp2f(-g * LOG2E)); }
;     __device__ __forceinline__ void operator()(const f32x4 (&acc)[2][2][4][2], const pg8::Unit& u, int wr, int wc, int fr, int fq) const {
;     ...
;             for (int m = 0; m < 4; ++m) {
;                 const int row = row0 + ai * 128 + m * 16;
;                 float s = ss_scale(ss, row);
;                 if constexpr (NN) s *= __builtin_amdgcn_rsqf(s * s * (float)ssw[row] * (1.f / 4294967296.f / 1024.f) + EPS);
;                 float a[8];
; #pragma unroll
;                 for (int n = 0; n < 2; ++n)
; #pragma unroll
;                     for (int i = 0; i < 4; ++i) { const float g = acc[ai][0][m][n][i] * s, uu = acc[ai][1][m][n][i] * s; a[4 * n + i] = silu_f(g) * uu; }
;                 u32x4 w; w.x = pkbf(a[0], a[1]); w.y = pkbf(a[2], a[3]); w.z = pkbf(a[4], a[5]); w.w = pkbf(a[6], a[7]);
;                 *(u32x4*)(O + (size_t)row * FF + col0) = w;
	v_cvt_f32_u32_e32 v166, v183
	v_cvt_f32_u32_e32 v167, v182
	v_fmamk_f32 v166, v166, 0x4f800000, v167
	v_fmamk_f32 v166, v166, 0x2a800000, v159
	v_rsq_f32_e32 v166, v166
	s_nop 0
	v_mul_f32_e32 v160, 0xbfb8aa3b, v166
	v_mul_f32_e32 v162, v166, v166
	v_pk_mul_f32 v[168:169], v[76:77], v[160:161] op_sel_hi:[1,0]
	v_pk_mul_f32 v[170:171], v[78:79], v[160:161] op_sel_hi:[1,0]
	v_pk_mul_f32 v[172:173], v[72:73], v[160:161] op_sel_hi:[1,0]
	v_pk_mul_f32 v[174:175], v[74:75], v[160:161] op_sel_hi:[1,0]
	v_exp_f32_e32 v168, v168
	v_exp_f32_e32 v169, v169
	v_exp_f32_e32 v170, v170
	v_exp_f32_e32 v171, v171
	v_exp_f32_e32 v172, v172
	v_exp_f32_e32 v173, v173
	v_exp_f32_e32 v174, v174
	v_exp_f32_e32 v175, v175
	v_pk_add_f32 v[168:169], v[168:169], v[164:165]
	v_pk_add_f32 v[170:171], v[170:171], v[164:165]
	v_pk_add_f32 v[172:173], v[172:173], v[164:165]
	v_pk_add_f32 v[174:175], v[174:175], v[164:165]
	v_rcp_f32_e32 v168, v168
	v_rcp_f32_e32 v169, v169
	v_rcp_f32_e32 v170, v170
	v_rcp_f32_e32 v171, v171
	v_rcp_f32_e32 v172, v172
	v_rcp_f32_e32 v173, v173
	v_rcp_f32_e32 v174, v174
	v_rcp_f32_e32 v175, v175
	v_pk_mul_f32 v[76:77], v[76:77], v[68:69]
	v_pk_mul_f32 v[78:79], v[78:79], v[70:71]
	v_pk_mul_f32 v[72:73], v[72:73], v[64:65]
	v_pk_mul_f32 v[74:75], v[74:75], v[66:67]
	v_pk_mul_f32 v[76:77], v[76:77], v[168:169]
	v_pk_mul_f32 v[78:79], v[78:79], v[170:171]
	v_pk_mul_f32 v[72:73], v[72:73], v[172:173]
	v_pk_mul_f32 v[74:75], v[74:75], v[174:175]
	v_pk_mul_f32 v[76:77], v[76:77], v[162:163] op_sel_hi:[1,0]
	v_pk_mul_f32 v[78:79], v[78:79], v[162:163] op_sel_hi:[1,0]
	v_pk_mul_f32 v[72:73], v[72:73], v[162:163] op_sel_hi:[1,0]
	v_pk_mul_f32 v[74:75], v[74:75], v[162:163] op_sel_hi:[1,0]
	v_cvt_pk_bf16_f32 v68, v76, v77
	v_cvt_pk_bf16_f32 v69, v78, v79
	v_cvt_pk_bf16_f32 v70, v72, v73
	v_cvt_pk_bf16_f32 v71, v74, v75
	s_mov_b32 s100, 0x42000
	v_lshl_add_u64 v[148:149], v[146:147], 0, s[100:101]
	global_store_dwordx4 v[148:149], v[68:71], off
	s_waitcnt vmcnt(7)
	v_cvt_f32_u32_e32 v166, v185
	v_cvt_f32_u32_e32 v167, v184
	v_fmamk_f32 v166, v166, 0x4f800000, v167
	v_fmamk_f32 v166, v166, 0x2a800000, v159
	v_rsq_f32_e32 v166, v166
	s_nop 0
	v_mul_f32_e32 v160, 0xbfb8aa3b, v166
	v_mul_f32_e32 v162, v166, v166
	v_pk_mul_f32 v[168:169], v[60:61], v[160:161] op_sel_hi:[1,0]
	v_pk_mul_f32 v[170:171], v[62:63], v[160:161] op_sel_hi:[1,0]
	v_pk_mul_f32 v[172:173], v[56:57], v[160:161] op_sel_hi:[1,0]
	v_pk_mul_f32 v[174:175], v[58:59], v[160:161] op_sel_hi:[1,0]
	v_exp_f32_e32 v168, v168
	v_exp_f32_e32 v169, v169
	v_exp_f32_e32 v170, v170
	v_exp_f32_e32 v171, v171
	v_exp_f32_e32 v172, v172
	v_exp_f32_e32 v173, v173
	v_exp_f32_e32 v174, v174
	v_exp_f32_e32 v175, v175
	v_pk_add_f32 v[168:169], v[168:169], v[164:165]
	v_pk_add_f32 v[170:171], v[170:171], v[164:165]
	v_pk_add_f32 v[172:173], v[172:173], v[164:165]
	v_pk_add_f32 v[174:175], v[174:175], v[164:165]
	v_rcp_f32_e32 v168, v168
	v_rcp_f32_e32 v169, v169
	v_rcp_f32_e32 v170, v170
	v_rcp_f32_e32 v171, v171
	v_rcp_f32_e32 v172, v172
	v_rcp_f32_e32 v173, v173
	v_rcp_f32_e32 v174, v174
	v_rcp_f32_e32 v175, v175
	v_pk_mul_f32 v[60:61], v[60:61], v[52:53]
	v_pk_mul_f32 v[62:63], v[62:63], v[54:55]
	v_pk_mul_f32 v[56:57], v[56:57], v[48:49]
	v_pk_mul_f32 v[58:59], v[58:59], v[50:51]
	v_pk_mul_f32 v[60:61], v[60:61], v[168:169]
	v_pk_mul_f32 v[62:63], v[62:63], v[170:171]
	v_pk_mul_f32 v[56:57], v[56:57], v[172:173]
	v_pk_mul_f32 v[58:59], v[58:59], v[174:175]
	v_pk_mul_f32 v[60:61], v[60:61], v[162:163] op_sel_hi:[1,0]
	v_pk_mul_f32 v[62:63], v[62:63], v[162:163] op_sel_hi:[1,0]
	v_pk_mul_f32 v[56:57], v[56:57], v[162:163] op_sel_hi:[1,0]
	v_pk_mul_f32 v[58:59], v[58:59], v[162:163] op_sel_hi:[1,0]
	v_cvt_pk_bf16_f32 v52, v60, v61
	v_cvt_pk_bf16_f32 v53, v62, v63
	v_cvt_pk_bf16_f32 v54, v56, v57
	v_cvt_pk_bf16_f32 v55, v58, v59
	s_mov_b32 s100, 0xb0000
	v_lshl_add_u64 v[148:149], v[146:147], 0, s[100:101]
	global_store_dwordx4 v[148:149], v[52:55], off
	s_waitcnt vmcnt(7)
	v_cvt_f32_u32_e32 v166, v187
	v_cvt_f32_u32_e32 v167, v186
	v_fmamk_f32 v166, v166, 0x4f800000, v167
	v_fmamk_f32 v166, v166, 0x2a800000, v159
	v_rsq_f32_e32 v166, v166
	s_nop 0
	v_mul_f32_e32 v160, 0xbfb8aa3b, v166
	v_mul_f32_e32 v162, v166, v166
	v_pk_mul_f32 v[168:169], v[44:45], v[160:161] op_sel_hi:[1,0]
	v_pk_mul_f32 v[170:171], v[46:47], v[160:161] op_sel_hi:[1,0]
	v_pk_mul_f32 v[172:173], v[40:41], v[160:161] op_sel_hi:[1,0]
	v_pk_mul_f32 v[174:175], v[42:43], v[160:161] op_sel_hi:[1,0]
	v_exp_f32_e32 v168, v168
	v_exp_f32_e32 v169, v169
	v_exp_f32_e32 v170, v170
	v_exp_f32_e32 v171, v171
	v_exp_f32_e32 v172, v172
	v_exp_f32_e32 v173, v173
	v_exp_f32_e32 v174, v174
	v_exp_f32_e32 v175, v175
	v_pk_add_f32 v[168:169], v[168:169], v[164:165]
	v_pk_add_f32 v[170:171], v[170:171], v[164:165]
	v_pk_add_f32 v[172:173], v[172:173], v[164:165]
	v_pk_add_f32 v[174:175], v[174:175], v[164:165]
	v_rcp_f32_e32 v168, v168
	v_rcp_f32_e32 v169, v169
	v_rcp_f32_e32 v170, v170
	v_rcp_f32_e32 v171, v171
	v_rcp_f32_e32 v172, v172
	v_rcp_f32_e32 v173, v173
	v_rcp_f32_e32 v174, v174
	v_rcp_f32_e32 v175, v175
	v_pk_mul_f32 v[44:45], v[44:45], v[36:37]
	v_pk_mul_f32 v[46:47], v[46:47], v[38:39]
	v_pk_mul_f32 v[40:41], v[40:41], v[32:33]
	v_pk_mul_f32 v[42:43], v[42:43], v[34:35]
	v_pk_mul_f32 v[44:45], v[44:45], v[168:169]
	v_pk_mul_f32 v[46:47], v[46:47], v[170:171]
	v_pk_mul_f32 v[40:41], v[40:41], v[172:173]
	v_pk_mul_f32 v[42:43], v[42:43], v[174:175]
	v_pk_mul_f32 v[44:45], v[44:45], v[162:163] op_sel_hi:[1,0]
	v_pk_mul_f32 v[46:47], v[46:47], v[162:163] op_sel_hi:[1,0]
	v_pk_mul_f32 v[40:41], v[40:41], v[162:163] op_sel_hi:[1,0]
	v_pk_mul_f32 v[42:43], v[42:43], v[162:163] op_sel_hi:[1,0]
	v_cvt_pk_bf16_f32 v36, v44, v45
	v_cvt_pk_bf16_f32 v37, v46, v47
	v_cvt_pk_bf16_f32 v38, v40, v41
	v_cvt_pk_bf16_f32 v39, v42, v43
	s_mov_b32 s100, 0xc6000
	v_lshl_add_u64 v[148:149], v[146:147], 0, s[100:101]
	global_store_dwordx4 v[148:149], v[36:39], off
	s_waitcnt vmcnt(7)
; __device__ __forceinline__ float ss_scale(const u64* ss, int row) { return __builtin_amdgcn_rsqf((float)ss[row] * (1.f / 4294967296.f / 1024.f) + EPS); }
; __device__ __forceinline__ unsigned pkbf(float lo, float hi) { typedef __bf16 bf2_t __attribute__((ext_vector_type(2))); f32x2 v = {lo, hi}; bf2_t b = __builtin_convertvector(v, bf2_t); return __builtin_bit_cast(unsigned, b); }
; __device__ __forceinline__ float silu_f(float g) { return g * __builtin_amdgcn_rcpf(1.f + __builtin_amdgcn_exp2f(-g * LOG2E)); }
;     __device__ __forceinline__ void operator()(const f32x4 (&acc)[2][2][4][2], const pg8::Unit& u, int wr, int wc, int fr, int fq) const {
;     ...
;             for (int m = 0; m < 4; ++m) {
;                 const int row = row0 + ai * 128 + m * 16;
;                 float s = ss_scale(ss, row);
;                 if constexpr (NN) s *= __builtin_amdgcn_rsqf(s * s * (float)ssw[row] * (1.f / 4294967296.f / 1024.f) + EPS);
;                 float a[8];
; #pragma unroll
;                 for (int n = 0; n < 2; ++n)
; #pragma unroll
;                     for (int i = 0; i < 4; ++i) { const float g = acc[ai][0][m][n][i] * s, uu = acc[ai][1][m][n][i] * s; a[4 * n + i] = silu_f(g) * uu; }
;                 u32x4 w; w.x = pkbf(a[0], a[1]); w.y = pkbf(a[2], a[3]); w.z = pkbf(a[4], a[5]); w.w = pkbf(a[6], a[7]);
;                 *(u32x4*)(O + (size_t)row * FF + col0) = w;
	v_cvt_f32_u32_e32 v166, v189
	v_cvt_f32_u32_e32 v167, v188
	v_fmamk_f32 v166, v166, 0x4f800000, v167
	v_fmamk_f32 v166, v166, 0x2a800000, v159
	v_rsq_f32_e32 v166, v166
	s_nop 0
	v_mul_f32_e32 v160, 0xbfb8aa3b, v166
	v_mul_f32_e32 v162, v166, v166
	v_pk_mul_f32 v[168:169], v[28:29], v[160:161] op_sel_hi:[1,0]
	v_pk_mul_f32 v[170:171], v[30:31], v[160:161] op_sel_hi:[1,0]
	v_pk_mul_f32 v[172:173], v[24:25], v[160:161] op_sel_hi:[1,0]
	v_pk_mul_f32 v[174:175], v[26:27], v[160:161] op_sel_hi:[1,0]
	v_exp_f32_e32 v168, v168
	v_exp_f32_e32 v169, v169
	v_exp_f32_e32 v170, v170
	v_exp_f32_e32 v171, v171
	v_exp_f32_e32 v172, v172
	v_exp_f32_e32 v173, v173
	v_exp_f32_e32 v174, v174
	v_exp_f32_e32 v175, v175
	v_pk_add_f32 v[168:169], v[168:169], v[164:165]
	v_pk_add_f32 v[170:171], v[170:171], v[164:165]
	v_pk_add_f32 v[172:173], v[172:173], v[164:165]
	v_pk_add_f32 v[174:175], v[174:175], v[164:165]
	v_rcp_f32_e32 v168, v168
	v_rcp_f32_e32 v169, v169
	v_rcp_f32_e32 v170, v170
	v_rcp_f32_e32 v171, v171
	v_rcp_f32_e32 v172, v172
	v_rcp_f32_e32 v173, v173
	v_rcp_f32_e32 v174, v174
	v_rcp_f32_e32 v175, v175
	v_pk_mul_f32 v[28:29], v[28:29], v[20:21]
	v_pk_mul_f32 v[30:31], v[30:31], v[22:23]
	v_pk_mul_f32 v[24:25], v[24:25], v[16:17]
	v_pk_mul_f32 v[26:27], v[26:27], v[18:19]
	v_pk_mul_f32 v[28:29], v[28:29], v[168:169]
	v_pk_mul_f32 v[30:31], v[30:31], v[170:171]
	v_pk_mul_f32 v[24:25], v[24:25], v[172:173]
	v_pk_mul_f32 v[26:27], v[26:27], v[174:175]
	v_pk_mul_f32 v[28:29], v[28:29], v[162:163] op_sel_hi:[1,0]
	v_pk_mul_f32 v[30:31], v[30:31], v[162:163] op_sel_hi:[1,0]
	v_pk_mul_f32 v[24:25], v[24:25], v[162:163] op_sel_hi:[1,0]
	v_pk_mul_f32 v[26:27], v[26:27], v[162:163] op_sel_hi:[1,0]
	v_cvt_pk_bf16_f32 v20, v28, v29
	v_cvt_pk_bf16_f32 v21, v30, v31
	v_cvt_pk_bf16_f32 v22, v24, v25
	v_cvt_pk_bf16_f32 v23, v26, v27
	s_mov_b32 s100, 0xdc000
	v_lshl_add_u64 v[148:149], v[146:147], 0, s[100:101]
	global_store_dwordx4 v[148:149], v[20:23], off
	s_waitcnt vmcnt(7)
	v_cvt_f32_u32_e32 v166, v191
	v_cvt_f32_u32_e32 v167, v190
	v_fmamk_f32 v166, v166, 0x4f800000, v167
	v_fmamk_f32 v166, v166, 0x2a800000, v159
	v_rsq_f32_e32 v166, v166
	s_nop 0
	v_mul_f32_e32 v160, 0xbfb8aa3b, v166
	v_mul_f32_e32 v162, v166, v166
	v_pk_mul_f32 v[168:169], v[12:13], v[160:161] op_sel_hi:[1,0]
	v_pk_mul_f32 v[170:171], v[14:15], v[160:161] op_sel_hi:[1,0]
	v_pk_mul_f32 v[172:173], v[8:9], v[160:161] op_sel_hi:[1,0]
	v_pk_mul_f32 v[174:175], v[10:11], v[160:161] op_sel_hi:[1,0]
	v_exp_f32_e32 v168, v168
	v_exp_f32_e32 v169, v169
	v_exp_f32_e32 v170, v170
	v_exp_f32_e32 v171, v171
	v_exp_f32_e32 v172, v172
	v_exp_f32_e32 v173, v173
	v_exp_f32_e32 v174, v174
	v_exp_f32_e32 v175, v175
	v_pk_add_f32 v[168:169], v[168:169], v[164:165]
	v_pk_add_f32 v[170:171], v[170:171], v[164:165]
	v_pk_add_f32 v[172:173], v[172:173], v[164:165]
	v_pk_add_f32 v[174:175], v[174:175], v[164:165]
	v_rcp_f32_e32 v168, v168
	v_rcp_f32_e32 v169, v169
	v_rcp_f32_e32 v170, v170
	v_rcp_f32_e32 v171, v171
	v_rcp_f32_e32 v172, v172
	v_rcp_f32_e32 v173, v173
	v_rcp_f32_e32 v174, v174
	v_rcp_f32_e32 v175, v175
	v_pk_mul_f32 v[12:13], v[12:13], v[4:5]
	v_pk_mul_f32 v[14:15], v[14:15], v[6:7]
	v_pk_mul_f32 v[8:9], v[8:9], v[0:1]
	v_pk_mul_f32 v[10:11], v[10:11], v[2:3]
	v_pk_mul_f32 v[12:13], v[12:13], v[168:169]
	v_pk_mul_f32 v[14:15], v[14:15], v[170:171]
	v_pk_mul_f32 v[8:9], v[8:9], v[172:173]
	v_pk_mul_f32 v[10:11], v[10:11], v[174:175]
	v_pk_mul_f32 v[12:13], v[12:13], v[162:163] op_sel_hi:[1,0]
	v_pk_mul_f32 v[14:15], v[14:15], v[162:163] op_sel_hi:[1,0]
	v_pk_mul_f32 v[8:9], v[8:9], v[162:163] op_sel_hi:[1,0]
	v_pk_mul_f32 v[10:11], v[10:11], v[162:163] op_sel_hi:[1,0]
	v_cvt_pk_bf16_f32 v4, v12, v13
	v_cvt_pk_bf16_f32 v5, v14, v15
	v_cvt_pk_bf16_f32 v6, v8, v9
	v_cvt_pk_bf16_f32 v7, v10, v11
	s_mov_b32 s100, 0xf2000
	v_lshl_add_u64 v[148:149], v[146:147], 0, s[100:101]
	global_store_dwordx4 v[148:149], v[4:7], off
	s_cbranch_vccnz .LBB0_275
	s_andn2_b64 vcc, exec, s[4:5]
	s_cbranch_vccnz .LBB0_274
	s_barrier
	s_branch .LBB0_274

; #define PG8_STAGE(bufoff, gbase, voff) do { _Pragma("unroll") for (int _i = 0; _i < 2; ++_i) \
;         __builtin_amdgcn_global_load_lds((const unsigned*)((const char*)(gbase) + (voff)[_i]), (PG8_LAS unsigned*)(lds + (bufoff) + ldsw + _i * 8192), 16, 0, 0); } while (0)
; #define PG8_LDA(dst, b, h) do { _Pragma("unroll") for (int m = 0; m < 4; ++m) _Pragma("unroll") for (int k = 0; k < 2; ++k) dst[m][k] = *(const PG8_LAS bf16x8*)(lds + PG8_SA(b, h) + aoff + m * 2048 + k * 1024); } while (0)
; #define PG8_LDB(dst, b, h) do { _Pragma("unroll") for (int n = 0; n < 2; ++n) _Pragma("unroll") for (int k = 0; k < 2; ++k) dst[n][k] = *(const PG8_LAS bf16x8*)(lds + PG8_SB(b, h) + boff + n * 2048 + k * 1024); } while (0)
; #define PG8_MMA(ai, bj, At, Bt) do { __builtin_amdgcn_s_setprio(1); _Pragma("unroll") for (int m = 0; m < 4; ++m) _Pragma("unroll") for (int n = 0; n < 2; ++n) _Pragma("unroll") for (int k = 0; k < 2; ++k) \
;         acc[ai][bj][m][n] = __builtin_amdgcn_mfma_f32_16x16x32_bf16(Bt[n][k], At[m][k], acc[ai][bj][m][n], 0, 0, 0); __builtin_amdgcn_s_setprio(0); } while (0)
; #define PG8_WAIT_V(n) asm volatile("s_waitcnt vmcnt(" #n ")" ::: "memory")
; #define PG8_WAIT_L(n) asm volatile("s_waitcnt lgkmcnt(" #n ")" ::: "memory")
; #define PG8_BAR __builtin_amdgcn_s_barrier()
; #define PG8_SCHED __builtin_amdgcn_sched_barrier(0)
; template <class Epi, class Sched, bool ALIGN_EPI = false, bool SP2 = false>
; __device__ __forceinline__ void gemm_phase(PG8_LAS unsigned char* lds, const Gemm g, const Sched& S, const Epi& E, const int tid) {
;     ...
;             PG8_LDB(B0, 0, 0); PG8_LDB(B1, 0, 1); PG8_SCHED; PG8_LDA(At, 0, 0); PG8_STAGE(PG8_SA(1, 1), a1 + hstepA, voffA);
;             PG8_WAIT_V(8); PG8_WAIT_L(0); PG8_BAR; PG8_MMA(0, 0, At, B0); PG8_MMA(0, 1, At, B1); PG8_BAR; PG8_SCHED;
;             PG8_LDA(At, 0, 1); PG8_STAGE(PG8_SB(0, 0), b2, voffB); PG8_STAGE(PG8_SB(0, 1), b2 + hstep, voffB); PG8_STAGE(PG8_SA(0, 0), a2, voffA);
;             PG8_WAIT_V(8); PG8_WAIT_L(0); PG8_BAR; PG8_MMA(1, 0, At, B0); PG8_MMA(1, 1, At, B1); PG8_BAR; PG8_SCHED;
.LBB0_849:
	ds_read_b128 v[144:147], v154
	ds_read_b128 v[148:151], v154 offset:1024
	ds_read_b128 v[160:163], v154 offset:2048
	ds_read_b128 v[164:167], v154 offset:3072
	ds_read_b128 v[168:171], v155
	ds_read_b128 v[172:175], v155 offset:1024
	ds_read_b128 v[176:179], v155 offset:2048
	ds_read_b128 v[180:183], v155 offset:3072
	s_add_u32 s26, s24, 0xfffc0080
	s_addc_u32 s27, s25, -1
	s_cmp_eq_u32 s58, 12
	s_cselect_b32 s29, s17, s27
	s_cselect_b32 s28, s54, s26
	s_cselect_b32 s27, s15, s57
	s_cselect_b32 s26, s55, s56
	v_lshl_add_u64 v[196:197], s[24:25], 0, v[136:137]
	s_add_i32 m0, s39, 0xc000
	ds_read_b128 v[184:187], v156
	ds_read_b128 v[188:191], v156 offset:1024
	ds_read_b128 v[192:195], v156 offset:2048
	ds_read_b128 v[200:203], v156 offset:3072
	ds_read_b128 v[204:207], v156 offset:4096
	ds_read_b128 v[208:211], v156 offset:5120
	ds_read_b128 v[212:215], v156 offset:6144
	ds_read_b128 v[216:219], v156 offset:7168
	global_load_lds_dwordx4 v[196:197], off
	v_lshl_add_u64 v[196:197], s[24:25], 0, v[138:139]
	s_add_i32 m0, s39, 0xe000
	s_nop 0
	global_load_lds_dwordx4 v[196:197], off
	s_waitcnt vmcnt(8)
	s_waitcnt lgkmcnt(0)
	s_barrier
	s_setprio 1
	s_waitcnt lgkmcnt(0)
	v_mfma_f32_16x16x32_bf16 v[124:127], v[144:147], v[184:187], v[124:127]
	v_mfma_f32_16x16x32_bf16 v[120:123], v[160:163], v[184:187], v[120:123]
	v_mfma_f32_16x16x32_bf16 v[108:111], v[144:147], v[192:195], v[108:111]
	v_mfma_f32_16x16x32_bf16 v[104:107], v[160:163], v[192:195], v[104:107]
	v_mfma_f32_16x16x32_bf16 v[92:95], v[144:147], v[204:207], v[92:95]
	v_mfma_f32_16x16x32_bf16 v[88:91], v[160:163], v[204:207], v[88:91]
	v_mfma_f32_16x16x32_bf16 v[76:79], v[144:147], v[212:215], v[76:79]
	v_mfma_f32_16x16x32_bf16 v[72:75], v[160:163], v[212:215], v[72:75]
	v_mfma_f32_16x16x32_bf16 v[124:127], v[148:151], v[188:191], v[124:127]
	v_mfma_f32_16x16x32_bf16 v[120:123], v[164:167], v[188:191], v[120:123]
	v_mfma_f32_16x16x32_bf16 v[108:111], v[148:151], v[200:203], v[108:111]
	v_mfma_f32_16x16x32_bf16 v[104:107], v[164:167], v[200:203], v[104:107]
	v_mfma_f32_16x16x32_bf16 v[92:95], v[148:151], v[208:211], v[92:95]
	v_mfma_f32_16x16x32_bf16 v[88:91], v[164:167], v[208:211], v[88:91]
	v_mfma_f32_16x16x32_bf16 v[76:79], v[148:151], v[216:219], v[76:79]
	v_mfma_f32_16x16x32_bf16 v[72:75], v[164:167], v[216:219], v[72:75]
	s_setprio 0
	s_setprio 1
	v_mfma_f32_16x16x32_bf16 v[116:119], v[168:171], v[184:187], v[116:119]
	v_mfma_f32_16x16x32_bf16 v[112:115], v[176:179], v[184:187], v[112:115]
	v_mfma_f32_16x16x32_bf16 v[100:103], v[168:171], v[192:195], v[100:103]
	v_mfma_f32_16x16x32_bf16 v[96:99], v[176:179], v[192:195], v[96:99]
	v_mfma_f32_16x16x32_bf16 v[84:87], v[168:171], v[204:207], v[84:87]
	v_mfma_f32_16x16x32_bf16 v[80:83], v[176:179], v[204:207], v[80:83]
	v_mfma_f32_16x16x32_bf16 v[68:71], v[168:171], v[212:215], v[68:71]
	v_mfma_f32_16x16x32_bf16 v[64:67], v[176:179], v[212:215], v[64:67]
	v_mfma_f32_16x16x32_bf16 v[116:119], v[172:175], v[188:191], v[116:119]
	v_mfma_f32_16x16x32_bf16 v[112:115], v[180:183], v[188:191], v[112:115]
	v_mfma_f32_16x16x32_bf16 v[100:103], v[172:175], v[200:203], v[100:103]
	v_mfma_f32_16x16x32_bf16 v[96:99], v[180:183], v[200:203], v[96:99]
	v_mfma_f32_16x16x32_bf16 v[84:87], v[172:175], v[208:211], v[84:87]
	v_mfma_f32_16x16x32_bf16 v[80:83], v[180:183], v[208:211], v[80:83]
	v_mfma_f32_16x16x32_bf16 v[68:71], v[172:175], v[216:219], v[68:71]
	v_mfma_f32_16x16x32_bf16 v[64:67], v[180:183], v[216:219], v[64:67]
	s_setprio 0
	s_barrier
	s_mov_b32 m0, s23
	v_lshl_add_u64 v[196:197], s[26:27], 0, v[132:133]
	s_add_u32 s60, s26, 0x40000
	ds_read_b128 v[184:187], v156 offset:16384
	ds_read_b128 v[188:191], v156 offset:17408
	ds_read_b128 v[192:195], v156 offset:18432
	ds_read_b128 v[200:203], v156 offset:19456
	ds_read_b128 v[204:207], v156 offset:20480
	ds_read_b128 v[208:211], v156 offset:21504
	ds_read_b128 v[212:215], v156 offset:22528
	ds_read_b128 v[216:219], v156 offset:23552
	global_load_lds_dwordx4 v[196:197], off
	v_lshl_add_u64 v[220:221], s[26:27], 0, v[128:129]
	s_mov_b32 m0, s36
	s_addc_u32 s61, s27, 0
	global_load_lds_dwordx4 v[220:221], off
	v_lshl_add_u64 v[222:223], s[60:61], 0, v[132:133]
	s_mov_b32 m0, s37
	v_lshl_add_u64 v[224:225], s[28:29], 0, v[130:131]
	global_load_lds_dwordx4 v[222:223], off
	v_lshl_add_u64 v[222:223], s[60:61], 0, v[128:129]
	s_mov_b32 m0, s38
	s_nop 0
	global_load_lds_dwordx4 v[222:223], off
	v_lshl_add_u64 v[222:223], s[28:29], 0, v[134:135]
	s_mov_b32 m0, s39
	s_nop 0
	global_load_lds_dwordx4 v[222:223], off
	s_mov_b32 m0, s40
	s_nop 0
	global_load_lds_dwordx4 v[224:225], off
	s_waitcnt vmcnt(8)
	s_waitcnt lgkmcnt(0)
	s_barrier
; #define PG8_STAGE(bufoff, gbase, voff) do { _Pragma("unroll") for (int _i = 0; _i < 2; ++_i) \
;         __builtin_amdgcn_global_load_lds((const unsigned*)((const char*)(gbase) + (voff)[_i]), (PG8_LAS unsigned*)(lds + (bufoff) + ldsw + _i * 8192), 16, 0, 0); } while (0)
; #define PG8_LDA(dst, b, h) do { _Pragma("unroll") for (int m = 0; m < 4; ++m) _Pragma("unroll") for (int k = 0; k < 2; ++k) dst[m][k] = *(const PG8_LAS bf16x8*)(lds + PG8_SA(b, h) + aoff + m * 2048 + k * 1024); } while (0)
; #define PG8_LDB(dst, b, h) do { _Pragma("unroll") for (int n = 0; n < 2; ++n) _Pragma("unroll") for (int k = 0; k < 2; ++k) dst[n][k] = *(const PG8_LAS bf16x8*)(lds + PG8_SB(b, h) + boff + n * 2048 + k * 1024); } while (0)
; #define PG8_MMA(ai, bj, At, Bt) do { __builtin_amdgcn_s_setprio(1); _Pragma("unroll") for (int m = 0; m < 4; ++m) _Pragma("unroll") for (int n = 0; n < 2; ++n) _Pragma("unroll") for (int k = 0; k < 2; ++k) \
;         acc[ai][bj][m][n] = __builtin_amdgcn_mfma_f32_16x16x32_bf16(Bt[n][k], At[m][k], acc[ai][bj][m][n], 0, 0, 0); __builtin_amdgcn_s_setprio(0); } while (0)
; #define PG8_WAIT_V(n) asm volatile("s_waitcnt vmcnt(" #n ")" ::: "memory")
; #define PG8_WAIT_L(n) asm volatile("s_waitcnt lgkmcnt(" #n ")" ::: "memory")
; #define PG8_BAR __builtin_amdgcn_s_barrier()
; #define PG8_SCHED __builtin_amdgcn_sched_barrier(0)
; template <class Epi, class Sched, bool ALIGN_EPI = false, bool SP2 = false>
; __device__ __forceinline__ void gemm_phase(PG8_LAS unsigned char* lds, const Gemm g, const Sched& S, const Epi& E, const int tid) {
;     ...
;             PG8_WAIT_V(8); PG8_WAIT_L(0); PG8_BAR; PG8_MMA(1, 0, At, B0); PG8_MMA(1, 1, At, B1); PG8_BAR; PG8_SCHED;
;             PG8_LDB(B0, 1, 0); PG8_LDB(B1, 1, 1); PG8_SCHED; PG8_LDA(At, 1, 0); PG8_STAGE(PG8_SA(0, 1), a2 + hstepA, voffA);
;             PG8_WAIT_V(8); PG8_WAIT_L(0); PG8_BAR; PG8_MMA(0, 0, At, B0); PG8_MMA(0, 1, At, B1); PG8_BAR; PG8_SCHED;
	s_setprio 1
	s_waitcnt lgkmcnt(0)
	v_mfma_f32_16x16x32_bf16 v[60:63], v[144:147], v[184:187], v[60:63]
	v_mfma_f32_16x16x32_bf16 v[56:59], v[160:163], v[184:187], v[56:59]
	v_mfma_f32_16x16x32_bf16 v[44:47], v[144:147], v[192:195], v[44:47]
	v_mfma_f32_16x16x32_bf16 v[40:43], v[160:163], v[192:195], v[40:43]
	v_mfma_f32_16x16x32_bf16 v[28:31], v[144:147], v[204:207], v[28:31]
	v_mfma_f32_16x16x32_bf16 v[24:27], v[160:163], v[204:207], v[24:27]
	v_mfma_f32_16x16x32_bf16 v[12:15], v[144:147], v[212:215], v[12:15]
	v_mfma_f32_16x16x32_bf16 v[8:11], v[160:163], v[212:215], v[8:11]
	v_mfma_f32_16x16x32_bf16 v[60:63], v[148:151], v[188:191], v[60:63]
	v_mfma_f32_16x16x32_bf16 v[56:59], v[164:167], v[188:191], v[56:59]
	v_mfma_f32_16x16x32_bf16 v[44:47], v[148:151], v[200:203], v[44:47]
	v_mfma_f32_16x16x32_bf16 v[40:43], v[164:167], v[200:203], v[40:43]
	v_mfma_f32_16x16x32_bf16 v[28:31], v[148:151], v[208:211], v[28:31]
	v_mfma_f32_16x16x32_bf16 v[24:27], v[164:167], v[208:211], v[24:27]
	v_mfma_f32_16x16x32_bf16 v[12:15], v[148:151], v[216:219], v[12:15]
	v_mfma_f32_16x16x32_bf16 v[8:11], v[164:167], v[216:219], v[8:11]
	s_setprio 0
	s_setprio 1
	v_mfma_f32_16x16x32_bf16 v[52:55], v[168:171], v[184:187], v[52:55]
	v_mfma_f32_16x16x32_bf16 v[48:51], v[176:179], v[184:187], v[48:51]
	v_mfma_f32_16x16x32_bf16 v[36:39], v[168:171], v[192:195], v[36:39]
	v_mfma_f32_16x16x32_bf16 v[32:35], v[176:179], v[192:195], v[32:35]
	v_mfma_f32_16x16x32_bf16 v[20:23], v[168:171], v[204:207], v[20:23]
	v_mfma_f32_16x16x32_bf16 v[16:19], v[176:179], v[204:207], v[16:19]
	v_mfma_f32_16x16x32_bf16 v[4:7], v[168:171], v[212:215], v[4:7]
	v_mfma_f32_16x16x32_bf16 v[0:3], v[176:179], v[212:215], v[0:3]
	v_mfma_f32_16x16x32_bf16 v[52:55], v[172:175], v[188:191], v[52:55]
	v_mfma_f32_16x16x32_bf16 v[48:51], v[180:183], v[188:191], v[48:51]
	v_mfma_f32_16x16x32_bf16 v[36:39], v[172:175], v[200:203], v[36:39]
	v_mfma_f32_16x16x32_bf16 v[32:35], v[180:183], v[200:203], v[32:35]
	v_mfma_f32_16x16x32_bf16 v[20:23], v[172:175], v[208:211], v[20:23]
	v_mfma_f32_16x16x32_bf16 v[16:19], v[180:183], v[208:211], v[16:19]
	v_mfma_f32_16x16x32_bf16 v[4:7], v[172:175], v[216:219], v[4:7]
	v_mfma_f32_16x16x32_bf16 v[0:3], v[180:183], v[216:219], v[0:3]
	s_setprio 0
	s_barrier
	ds_read_b128 v[144:147], v157
	ds_read_b128 v[148:151], v157 offset:1024
	ds_read_b128 v[160:163], v157 offset:2048
	ds_read_b128 v[164:167], v157 offset:3072
	ds_read_b128 v[168:171], v158
	ds_read_b128 v[172:175], v158 offset:1024
	ds_read_b128 v[176:179], v158 offset:2048
	ds_read_b128 v[180:183], v158 offset:3072
	s_add_u32 s28, s28, 0x40000
	s_addc_u32 s29, s29, 0
	s_mov_b32 m0, s41
	v_lshl_add_u64 v[226:227], s[28:29], 0, v[134:135]
	ds_read_b128 v[184:187], v156 offset:32768
	ds_read_b128 v[188:191], v156 offset:33792
	ds_read_b128 v[192:195], v156 offset:34816
	ds_read_b128 v[200:203], v156 offset:35840
	ds_read_b128 v[204:207], v156 offset:36864
	ds_read_b128 v[208:211], v156 offset:37888
	ds_read_b128 v[212:215], v156 offset:38912
	ds_read_b128 v[216:219], v156 offset:39936
	global_load_lds_dwordx4 v[226:227], off
	v_lshl_add_u64 v[226:227], s[28:29], 0, v[130:131]
	s_mov_b32 m0, s42
	s_nop 0
	global_load_lds_dwordx4 v[226:227], off
	s_waitcnt vmcnt(8)
	s_waitcnt lgkmcnt(0)
	s_barrier
	s_setprio 1
	s_waitcnt lgkmcnt(0)
	v_mfma_f32_16x16x32_bf16 v[124:127], v[144:147], v[184:187], v[124:127]
	v_mfma_f32_16x16x32_bf16 v[120:123], v[160:163], v[184:187], v[120:123]
	v_mfma_f32_16x16x32_bf16 v[108:111], v[144:147], v[192:195], v[108:111]
	v_mfma_f32_16x16x32_bf16 v[104:107], v[160:163], v[192:195], v[104:107]
	v_mfma_f32_16x16x32_bf16 v[92:95], v[144:147], v[204:207], v[92:95]
	v_mfma_f32_16x16x32_bf16 v[88:91], v[160:163], v[204:207], v[88:91]
	v_mfma_f32_16x16x32_bf16 v[76:79], v[144:147], v[212:215], v[76:79]
	v_mfma_f32_16x16x32_bf16 v[72:75], v[160:163], v[212:215], v[72:75]
	v_mfma_f32_16x16x32_bf16 v[124:127], v[148:151], v[188:191], v[124:127]
	v_mfma_f32_16x16x32_bf16 v[120:123], v[164:167], v[188:191], v[120:123]
	v_mfma_f32_16x16x32_bf16 v[108:111], v[148:151], v[200:203], v[108:111]
	v_mfma_f32_16x16x32_bf16 v[104:107], v[164:167], v[200:203], v[104:107]
	v_mfma_f32_16x16x32_bf16 v[92:95], v[148:151], v[208:211], v[92:95]
	v_mfma_f32_16x16x32_bf16 v[88:91], v[164:167], v[208:211], v[88:91]
	v_mfma_f32_16x16x32_bf16 v[76:79], v[148:151], v[216:219], v[76:79]
	v_mfma_f32_16x16x32_bf16 v[72:75], v[164:167], v[216:219], v[72:75]
	s_setprio 0
	s_setprio 1
	v_mfma_f32_16x16x32_bf16 v[116:119], v[168:171], v[184:187], v[116:119]
	v_mfma_f32_16x16x32_bf16 v[112:115], v[176:179], v[184:187], v[112:115]
	v_mfma_f32_16x16x32_bf16 v[100:103], v[168:171], v[192:195], v[100:103]
	v_mfma_f32_16x16x32_bf16 v[96:99], v[176:179], v[192:195], v[96:99]
	v_mfma_f32_16x16x32_bf16 v[84:87], v[168:171], v[204:207], v[84:87]
	v_mfma_f32_16x16x32_bf16 v[80:83], v[176:179], v[204:207], v[80:83]
	v_mfma_f32_16x16x32_bf16 v[68:71], v[168:171], v[212:215], v[68:71]
	v_mfma_f32_16x16x32_bf16 v[64:67], v[176:179], v[212:215], v[64:67]
	v_mfma_f32_16x16x32_bf16 v[116:119], v[172:175], v[188:191], v[116:119]
	v_mfma_f32_16x16x32_bf16 v[112:115], v[180:183], v[188:191], v[112:115]
	v_mfma_f32_16x16x32_bf16 v[100:103], v[172:175], v[200:203], v[100:103]
	v_mfma_f32_16x16x32_bf16 v[96:99], v[180:183], v[200:203], v[96:99]
	v_mfma_f32_16x16x32_bf16 v[84:87], v[172:175], v[208:211], v[84:87]
	v_mfma_f32_16x16x32_bf16 v[80:83], v[180:183], v[208:211], v[80:83]
	v_mfma_f32_16x16x32_bf16 v[68:71], v[172:175], v[216:219], v[68:71]
	v_mfma_f32_16x16x32_bf16 v[64:67], v[180:183], v[216:219], v[64:67]
	s_setprio 0
	s_barrier
; #define PG8_STAGE(bufoff, gbase, voff) do { _Pragma("unroll") for (int _i = 0; _i < 2; ++_i) \
;         __builtin_amdgcn_global_load_lds((const unsigned*)((const char*)(gbase) + (voff)[_i]), (PG8_LAS unsigned*)(lds + (bufoff) + ldsw + _i * 8192), 16, 0, 0); } while (0)
; #define PG8_LDA(dst, b, h) do { _Pragma("unroll") for (int m = 0; m < 4; ++m) _Pragma("unroll") for (int k = 0; k < 2; ++k) dst[m][k] = *(const PG8_LAS bf16x8*)(lds + PG8_SA(b, h) + aoff + m * 2048 + k * 1024); } while (0)
; #define PG8_MMA(ai, bj, At, Bt) do { __builtin_amdgcn_s_setprio(1); _Pragma("unroll") for (int m = 0; m < 4; ++m) _Pragma("unroll") for (int n = 0; n < 2; ++n) _Pragma("unroll") for (int k = 0; k < 2; ++k) \
;         acc[ai][bj][m][n] = __builtin_amdgcn_mfma_f32_16x16x32_bf16(Bt[n][k], At[m][k], acc[ai][bj][m][n], 0, 0, 0); __builtin_amdgcn_s_setprio(0); } while (0)
; #define PG8_WAIT_V(n) asm volatile("s_waitcnt vmcnt(" #n ")" ::: "memory")
; #define PG8_WAIT_L(n) asm volatile("s_waitcnt lgkmcnt(" #n ")" ::: "memory")
; #define PG8_BAR __builtin_amdgcn_s_barrier()
; #define PG8_SCHED __builtin_amdgcn_sched_barrier(0)
; __device__ __forceinline__ float ss_scale(const u64* ss, int row) { return __builtin_amdgcn_rsqf((float)ss[row] * (1.f / 4294967296.f / 1024.f) + EPS); }
; template <class Epi, class Sched, bool ALIGN_EPI = false, bool SP2 = false>
; __device__ __forceinline__ void gemm_phase(PG8_LAS unsigned char* lds, const Gemm g, const Sched& S, const Epi& E, const int tid) {
;     ...
;             PG8_LDA(At, 1, 1); PG8_STAGE(PG8_SB(1, 0), b3, voffB); PG8_STAGE(PG8_SB(1, 1), b3 + hstep, voffB); PG8_STAGE(PG8_SA(1, 0), a3, voffA);
;             PG8_WAIT_V(8); PG8_WAIT_L(0); PG8_BAR; PG8_MMA(1, 0, At, B0); PG8_MMA(1, 1, At, B1); PG8_BAR; PG8_SCHED;
;     __device__ __forceinline__ void operator()(const f32x4 (&acc)[2][2][4][2], const pg8::Unit& u, int wr, int wc, int fr, int fq) const {
;         const int row0 = u.pm * 256 + wr * 64 + fr, col0 = u.pn * 128 + wc * 32 + 8 * fq;
; #pragma unroll
;         for (int ai = 0; ai < 2; ++ai)
; #pragma unroll
;             for (int m = 0; m < 4; ++m) {
;                 const int row = row0 + ai * 128 + m * 16;
;                 float s = ss_scale(ss, row);
;                 if constexpr (NN) s *= __builtin_amdgcn_rsqf(s * s * (float)ssw[row] * (1.f / 4294967296.f / 1024.f) + EPS);
	s_mov_b32 m0, s45
	v_lshl_add_u64 v[196:197], v[196:197], 0, s[10:11]
	s_add_u32 s26, s26, 0x40080
	ds_read_b128 v[184:187], v156 offset:49152
	ds_read_b128 v[188:191], v156 offset:50176
	ds_read_b128 v[192:195], v156 offset:51200
	ds_read_b128 v[200:203], v156 offset:52224
	ds_read_b128 v[204:207], v156 offset:53248
	ds_read_b128 v[208:211], v156 offset:54272
	ds_read_b128 v[212:215], v156 offset:55296
	ds_read_b128 v[216:219], v156 offset:56320
	global_load_lds_dwordx4 v[196:197], off
	v_lshl_add_u64 v[196:197], v[220:221], 0, s[10:11]
	s_mov_b32 m0, s46
	s_addc_u32 s27, s27, 0
	global_load_lds_dwordx4 v[196:197], off
	v_lshl_add_u64 v[196:197], s[26:27], 0, v[132:133]
	s_mov_b32 m0, s49
	s_nop 0
	global_load_lds_dwordx4 v[196:197], off
	v_lshl_add_u64 v[196:197], s[26:27], 0, v[128:129]
	s_mov_b32 m0, s50
	s_nop 0
	global_load_lds_dwordx4 v[196:197], off
	v_lshl_add_u64 v[196:197], v[222:223], 0, s[10:11]
	s_mov_b32 m0, s47
	s_nop 0
	global_load_lds_dwordx4 v[196:197], off
	v_lshl_add_u64 v[196:197], v[224:225], 0, s[10:11]
	s_mov_b32 m0, s48
	s_nop 0
	global_load_lds_dwordx4 v[196:197], off
	s_waitcnt vmcnt(8)
	s_waitcnt lgkmcnt(0)
	s_barrier
	s_setprio 1
	s_waitcnt lgkmcnt(0)
	v_mfma_f32_16x16x32_bf16 v[60:63], v[144:147], v[184:187], v[60:63]
	v_mfma_f32_16x16x32_bf16 v[56:59], v[160:163], v[184:187], v[56:59]
	v_mfma_f32_16x16x32_bf16 v[44:47], v[144:147], v[192:195], v[44:47]
	v_mfma_f32_16x16x32_bf16 v[40:43], v[160:163], v[192:195], v[40:43]
	v_mfma_f32_16x16x32_bf16 v[28:31], v[144:147], v[204:207], v[28:31]
	v_mfma_f32_16x16x32_bf16 v[24:27], v[160:163], v[204:207], v[24:27]
	v_mfma_f32_16x16x32_bf16 v[12:15], v[144:147], v[212:215], v[12:15]
	v_mfma_f32_16x16x32_bf16 v[8:11], v[160:163], v[212:215], v[8:11]
	v_mfma_f32_16x16x32_bf16 v[60:63], v[148:151], v[188:191], v[60:63]
	v_mfma_f32_16x16x32_bf16 v[56:59], v[164:167], v[188:191], v[56:59]
	v_mfma_f32_16x16x32_bf16 v[44:47], v[148:151], v[200:203], v[44:47]
	v_mfma_f32_16x16x32_bf16 v[40:43], v[164:167], v[200:203], v[40:43]
	v_mfma_f32_16x16x32_bf16 v[28:31], v[148:151], v[208:211], v[28:31]
	v_mfma_f32_16x16x32_bf16 v[24:27], v[164:167], v[208:211], v[24:27]
	v_mfma_f32_16x16x32_bf16 v[12:15], v[148:151], v[216:219], v[12:15]
	v_mfma_f32_16x16x32_bf16 v[8:11], v[164:167], v[216:219], v[8:11]
	s_setprio 0
	s_setprio 1
	v_mfma_f32_16x16x32_bf16 v[52:55], v[168:171], v[184:187], v[52:55]
	v_mfma_f32_16x16x32_bf16 v[48:51], v[176:179], v[184:187], v[48:51]
	v_mfma_f32_16x16x32_bf16 v[36:39], v[168:171], v[192:195], v[36:39]
	v_mfma_f32_16x16x32_bf16 v[32:35], v[176:179], v[192:195], v[32:35]
	v_mfma_f32_16x16x32_bf16 v[20:23], v[168:171], v[204:207], v[20:23]
	v_mfma_f32_16x16x32_bf16 v[16:19], v[176:179], v[204:207], v[16:19]
	v_mfma_f32_16x16x32_bf16 v[4:7], v[168:171], v[212:215], v[4:7]
	v_mfma_f32_16x16x32_bf16 v[0:3], v[176:179], v[212:215], v[0:3]
	v_mfma_f32_16x16x32_bf16 v[52:55], v[172:175], v[188:191], v[52:55]
	v_mfma_f32_16x16x32_bf16 v[48:51], v[180:183], v[188:191], v[48:51]
	v_mfma_f32_16x16x32_bf16 v[36:39], v[172:175], v[200:203], v[36:39]
	v_mfma_f32_16x16x32_bf16 v[32:35], v[180:183], v[200:203], v[32:35]
	v_mfma_f32_16x16x32_bf16 v[20:23], v[172:175], v[208:211], v[20:23]
	v_mfma_f32_16x16x32_bf16 v[16:19], v[180:183], v[208:211], v[16:19]
	v_mfma_f32_16x16x32_bf16 v[4:7], v[172:175], v[216:219], v[4:7]
	v_mfma_f32_16x16x32_bf16 v[0:3], v[180:183], v[216:219], v[0:3]
	s_setprio 0
	s_barrier
	s_add_i32 s58, s58, 2
	s_add_u32 s24, s24, 0x100
	s_addc_u32 s25, s25, 0
	s_add_u32 s56, s56, 0x100
	s_addc_u32 s57, s57, 0
	s_cmp_gt_u32 s58, 13
	s_cbranch_scc0 .LBB0_849
	v_lshl_add_u32 v144, s22, 8, v152
	v_mov_b32_e32 v145, 0
	v_lshl_add_u64 v[150:151], v[144:145], 3, s[8:9]
	global_load_dwordx2 v[176:177], v[150:151], off
	global_load_dwordx2 v[178:179], v[150:151], off offset:128
	global_load_dwordx2 v[180:181], v[150:151], off offset:256
	global_load_dwordx2 v[182:183], v[150:151], off offset:384
	global_load_dwordx2 v[184:185], v[150:151], off offset:1024
	global_load_dwordx2 v[186:187], v[150:151], off offset:1152
	global_load_dwordx2 v[188:189], v[150:151], off offset:1280
	global_load_dwordx2 v[190:191], v[150:151], off offset:1408
	v_lshl_or_b32 v148, s53, 7, v153
	v_mul_u32_u24_e32 v146, s52, v144
	v_lshl_add_u32 v146, v148, 1, v146
	v_mov_b32_e32 v147, 0
	v_lshl_add_u64 v[146:147], v[146:147], 0, s[6:7]
	v_mov_b32_e32 v164, 1.0
	v_mov_b32_e32 v165, 1.0
	s_mov_b32 s101, 0
	s_and_b64 vcc, exec, s[12:13]
	s_cbranch_vccz .LBB0_852
	s_barrier

; #define PG8_STAGE(bufoff, gbase, voff) do { _Pragma("unroll") for (int _i = 0; _i < 2; ++_i) \
;         __builtin_amdgcn_global_load_lds((const unsigned*)((const char*)(gbase) + (voff)[_i]), (PG8_LAS unsigned*)(lds + (bufoff) + ldsw + _i * 8192), 16, 0, 0); } while (0)
; #define PG8_LDA(dst, b, h) do { _Pragma("unroll") for (int m = 0; m < 4; ++m) _Pragma("unroll") for (int k = 0; k < 2; ++k) dst[m][k] = *(const PG8_LAS bf16x8*)(lds + PG8_SA(b, h) + aoff + m * 2048 + k * 1024); } while (0)
; #define PG8_LDB(dst, b, h) do { _Pragma("unroll") for (int n = 0; n < 2; ++n) _Pragma("unroll") for (int k = 0; k < 2; ++k) dst[n][k] = *(const PG8_LAS bf16x8*)(lds + PG8_SB(b, h) + boff + n * 2048 + k * 1024); } while (0)
; #define PG8_MMA(ai, bj, At, Bt) do { __builtin_amdgcn_s_setprio(1); _Pragma("unroll") for (int m = 0; m < 4; ++m) _Pragma("unroll") for (int n = 0; n < 2; ++n) _Pragma("unroll") for (int k = 0; k < 2; ++k) \
;         acc[ai][bj][m][n] = __builtin_amdgcn_mfma_f32_16x16x32_bf16(Bt[n][k], At[m][k], acc[ai][bj][m][n], 0, 0, 0); __builtin_amdgcn_s_setprio(0); } while (0)
; #define PG8_WAIT_V(n) asm volatile("s_waitcnt vmcnt(" #n ")" ::: "memory")
; #define PG8_WAIT_L(n) asm volatile("s_waitcnt lgkmcnt(" #n ")" ::: "memory")
; #define PG8_BAR __builtin_amdgcn_s_barrier()
; #define PG8_SCHED __builtin_amdgcn_sched_barrier(0)
; template <class Epi, class Sched, bool ALIGN_EPI = false, bool SP2 = false>
; __device__ __forceinline__ void gemm_phase(PG8_LAS unsigned char* lds, const Gemm g, const Sched& S, const Epi& E, const int tid) {
;     ...
;             PG8_LDB(B0, 0, 0); PG8_LDB(B1, 0, 1); PG8_SCHED; PG8_LDA(At, 0, 0); PG8_STAGE(PG8_SA(1, 1), a1 + hstepA, voffA);
;             PG8_WAIT_V(8); PG8_WAIT_L(0); PG8_BAR; PG8_MMA(0, 0, At, B0); PG8_MMA(0, 1, At, B1); PG8_BAR; PG8_SCHED;
;             PG8_LDA(At, 0, 1); PG8_STAGE(PG8_SB(0, 0), b2, voffB); PG8_STAGE(PG8_SB(0, 1), b2 + hstep, voffB); PG8_STAGE(PG8_SA(0, 0), a2, voffA);
;             PG8_WAIT_V(8); PG8_WAIT_L(0); PG8_BAR; PG8_MMA(1, 0, At, B0); PG8_MMA(1, 1, At, B1); PG8_BAR; PG8_SCHED;
.LBB0_1007:
	ds_read_b128 v[144:147], v156
	ds_read_b128 v[148:151], v156 offset:1024
	ds_read_b128 v[162:165], v156 offset:2048
	ds_read_b128 v[166:169], v156 offset:3072
	ds_read_b128 v[170:173], v157
	ds_read_b128 v[174:177], v157 offset:1024
	ds_read_b128 v[178:181], v157 offset:2048
	ds_read_b128 v[182:185], v157 offset:3072
	s_add_u32 s28, s26, 0xfffc0080
	s_addc_u32 s29, s27, -1
	s_cmp_eq_u32 s60, 12
	s_cselect_b32 s31, s19, s29
	s_cselect_b32 s30, s56, s28
	s_cselect_b32 s29, s17, s59
	s_cselect_b32 s28, s57, s58
	v_lshl_add_u64 v[152:153], s[26:27], 0, v[136:137]
	s_add_i32 m0, s41, 0xc000
	ds_read_b128 v[186:189], v158
	ds_read_b128 v[190:193], v158 offset:1024
	ds_read_b128 v[194:197], v158 offset:2048
	ds_read_b128 v[200:203], v158 offset:3072
	ds_read_b128 v[204:207], v158 offset:4096
	ds_read_b128 v[208:211], v158 offset:5120
	ds_read_b128 v[212:215], v158 offset:6144
	ds_read_b128 v[216:219], v158 offset:7168
	global_load_lds_dwordx4 v[152:153], off
	v_lshl_add_u64 v[152:153], s[26:27], 0, v[138:139]
	s_add_i32 m0, s41, 0xe000
	s_nop 0
	global_load_lds_dwordx4 v[152:153], off
	s_waitcnt vmcnt(8)
	s_waitcnt lgkmcnt(0)
	s_barrier
	s_setprio 1
	s_waitcnt lgkmcnt(0)
	v_mfma_f32_16x16x32_bf16 v[124:127], v[144:147], v[186:189], v[124:127]
	v_mfma_f32_16x16x32_bf16 v[120:123], v[162:165], v[186:189], v[120:123]
	v_mfma_f32_16x16x32_bf16 v[108:111], v[144:147], v[194:197], v[108:111]
	v_mfma_f32_16x16x32_bf16 v[104:107], v[162:165], v[194:197], v[104:107]
	v_mfma_f32_16x16x32_bf16 v[92:95], v[144:147], v[204:207], v[92:95]
	v_mfma_f32_16x16x32_bf16 v[88:91], v[162:165], v[204:207], v[88:91]
	v_mfma_f32_16x16x32_bf16 v[76:79], v[144:147], v[212:215], v[76:79]
	v_mfma_f32_16x16x32_bf16 v[72:75], v[162:165], v[212:215], v[72:75]
	v_mfma_f32_16x16x32_bf16 v[124:127], v[148:151], v[190:193], v[124:127]
	v_mfma_f32_16x16x32_bf16 v[120:123], v[166:169], v[190:193], v[120:123]
	v_mfma_f32_16x16x32_bf16 v[108:111], v[148:151], v[200:203], v[108:111]
	v_mfma_f32_16x16x32_bf16 v[104:107], v[166:169], v[200:203], v[104:107]
	v_mfma_f32_16x16x32_bf16 v[92:95], v[148:151], v[208:211], v[92:95]
	v_mfma_f32_16x16x32_bf16 v[88:91], v[166:169], v[208:211], v[88:91]
	v_mfma_f32_16x16x32_bf16 v[76:79], v[148:151], v[216:219], v[76:79]
	v_mfma_f32_16x16x32_bf16 v[72:75], v[166:169], v[216:219], v[72:75]
	s_setprio 0
	s_setprio 1
	v_mfma_f32_16x16x32_bf16 v[116:119], v[170:173], v[186:189], v[116:119]
	v_mfma_f32_16x16x32_bf16 v[112:115], v[178:181], v[186:189], v[112:115]
	v_mfma_f32_16x16x32_bf16 v[100:103], v[170:173], v[194:197], v[100:103]
	v_mfma_f32_16x16x32_bf16 v[96:99], v[178:181], v[194:197], v[96:99]
	v_mfma_f32_16x16x32_bf16 v[84:87], v[170:173], v[204:207], v[84:87]
	v_mfma_f32_16x16x32_bf16 v[80:83], v[178:181], v[204:207], v[80:83]
	v_mfma_f32_16x16x32_bf16 v[68:71], v[170:173], v[212:215], v[68:71]
	v_mfma_f32_16x16x32_bf16 v[64:67], v[178:181], v[212:215], v[64:67]
	v_mfma_f32_16x16x32_bf16 v[116:119], v[174:177], v[190:193], v[116:119]
	v_mfma_f32_16x16x32_bf16 v[112:115], v[182:185], v[190:193], v[112:115]
	v_mfma_f32_16x16x32_bf16 v[100:103], v[174:177], v[200:203], v[100:103]
	v_mfma_f32_16x16x32_bf16 v[96:99], v[182:185], v[200:203], v[96:99]
	v_mfma_f32_16x16x32_bf16 v[84:87], v[174:177], v[208:211], v[84:87]
	v_mfma_f32_16x16x32_bf16 v[80:83], v[182:185], v[208:211], v[80:83]
	v_mfma_f32_16x16x32_bf16 v[68:71], v[174:177], v[216:219], v[68:71]
	v_mfma_f32_16x16x32_bf16 v[64:67], v[182:185], v[216:219], v[64:67]
	s_setprio 0
	s_barrier
	s_mov_b32 m0, s25
	v_lshl_add_u64 v[152:153], s[28:29], 0, v[132:133]
	s_add_u32 s62, s28, 0x40000
	ds_read_b128 v[186:189], v158 offset:16384
	ds_read_b128 v[190:193], v158 offset:17408
	ds_read_b128 v[194:197], v158 offset:18432
	ds_read_b128 v[200:203], v158 offset:19456
	ds_read_b128 v[204:207], v158 offset:20480
	ds_read_b128 v[208:211], v158 offset:21504
	ds_read_b128 v[212:215], v158 offset:22528
	ds_read_b128 v[216:219], v158 offset:23552
	global_load_lds_dwordx4 v[152:153], off
	v_lshl_add_u64 v[220:221], s[28:29], 0, v[128:129]
	s_mov_b32 m0, s38
	s_addc_u32 s63, s29, 0
	global_load_lds_dwordx4 v[220:221], off
	v_lshl_add_u64 v[222:223], s[62:63], 0, v[132:133]
	s_mov_b32 m0, s39
	v_lshl_add_u64 v[224:225], s[30:31], 0, v[130:131]
	global_load_lds_dwordx4 v[222:223], off
	v_lshl_add_u64 v[222:223], s[62:63], 0, v[128:129]
	s_mov_b32 m0, s40
	s_nop 0
	global_load_lds_dwordx4 v[222:223], off
	v_lshl_add_u64 v[222:223], s[30:31], 0, v[134:135]
	s_mov_b32 m0, s41
	s_nop 0
	global_load_lds_dwordx4 v[222:223], off
	s_mov_b32 m0, s42
	s_nop 0
	global_load_lds_dwordx4 v[224:225], off
	s_waitcnt vmcnt(8)
	s_waitcnt lgkmcnt(0)
	s_barrier
; #define PG8_STAGE(bufoff, gbase, voff) do { _Pragma("unroll") for (int _i = 0; _i < 2; ++_i) \
;         __builtin_amdgcn_global_load_lds((const unsigned*)((const char*)(gbase) + (voff)[_i]), (PG8_LAS unsigned*)(lds + (bufoff) + ldsw + _i * 8192), 16, 0, 0); } while (0)
; #define PG8_LDA(dst, b, h) do { _Pragma("unroll") for (int m = 0; m < 4; ++m) _Pragma("unroll") for (int k = 0; k < 2; ++k) dst[m][k] = *(const PG8_LAS bf16x8*)(lds + PG8_SA(b, h) + aoff + m * 2048 + k * 1024); } while (0)
; #define PG8_LDB(dst, b, h) do { _Pragma("unroll") for (int n = 0; n < 2; ++n) _Pragma("unroll") for (int k = 0; k < 2; ++k) dst[n][k] = *(const PG8_LAS bf16x8*)(lds + PG8_SB(b, h) + boff + n * 2048 + k * 1024); } while (0)
; #define PG8_MMA(ai, bj, At, Bt) do { __builtin_amdgcn_s_setprio(1); _Pragma("unroll") for (int m = 0; m < 4; ++m) _Pragma("unroll") for (int n = 0; n < 2; ++n) _Pragma("unroll") for (int k = 0; k < 2; ++k) \
;         acc[ai][bj][m][n] = __builtin_amdgcn_mfma_f32_16x16x32_bf16(Bt[n][k], At[m][k], acc[ai][bj][m][n], 0, 0, 0); __builtin_amdgcn_s_setprio(0); } while (0)
; #define PG8_WAIT_V(n) asm volatile("s_waitcnt vmcnt(" #n ")" ::: "memory")
; #define PG8_WAIT_L(n) asm volatile("s_waitcnt lgkmcnt(" #n ")" ::: "memory")
; #define PG8_BAR __builtin_amdgcn_s_barrier()
; #define PG8_SCHED __builtin_amdgcn_sched_barrier(0)
; template <class Epi, class Sched, bool ALIGN_EPI = false, bool SP2 = false>
; __device__ __forceinline__ void gemm_phase(PG8_LAS unsigned char* lds, const Gemm g, const Sched& S, const Epi& E, const int tid) {
;     ...
;             PG8_WAIT_V(8); PG8_WAIT_L(0); PG8_BAR; PG8_MMA(1, 0, At, B0); PG8_MMA(1, 1, At, B1); PG8_BAR; PG8_SCHED;
;             PG8_LDB(B0, 1, 0); PG8_LDB(B1, 1, 1); PG8_SCHED; PG8_LDA(At, 1, 0); PG8_STAGE(PG8_SA(0, 1), a2 + hstepA, voffA);
;             PG8_WAIT_V(8); PG8_WAIT_L(0); PG8_BAR; PG8_MMA(0, 0, At, B0); PG8_MMA(0, 1, At, B1); PG8_BAR; PG8_SCHED;
	s_setprio 1
	s_waitcnt lgkmcnt(0)
	v_mfma_f32_16x16x32_bf16 v[60:63], v[144:147], v[186:189], v[60:63]
	v_mfma_f32_16x16x32_bf16 v[56:59], v[162:165], v[186:189], v[56:59]
	v_mfma_f32_16x16x32_bf16 v[44:47], v[144:147], v[194:197], v[44:47]
	v_mfma_f32_16x16x32_bf16 v[40:43], v[162:165], v[194:197], v[40:43]
	v_mfma_f32_16x16x32_bf16 v[28:31], v[144:147], v[204:207], v[28:31]
	v_mfma_f32_16x16x32_bf16 v[24:27], v[162:165], v[204:207], v[24:27]
	v_mfma_f32_16x16x32_bf16 v[12:15], v[144:147], v[212:215], v[12:15]
	v_mfma_f32_16x16x32_bf16 v[8:11], v[162:165], v[212:215], v[8:11]
	v_mfma_f32_16x16x32_bf16 v[60:63], v[148:151], v[190:193], v[60:63]
	v_mfma_f32_16x16x32_bf16 v[56:59], v[166:169], v[190:193], v[56:59]
	v_mfma_f32_16x16x32_bf16 v[44:47], v[148:151], v[200:203], v[44:47]
	v_mfma_f32_16x16x32_bf16 v[40:43], v[166:169], v[200:203], v[40:43]
	v_mfma_f32_16x16x32_bf16 v[28:31], v[148:151], v[208:211], v[28:31]
	v_mfma_f32_16x16x32_bf16 v[24:27], v[166:169], v[208:211], v[24:27]
	v_mfma_f32_16x16x32_bf16 v[12:15], v[148:151], v[216:219], v[12:15]
	v_mfma_f32_16x16x32_bf16 v[8:11], v[166:169], v[216:219], v[8:11]
	s_setprio 0
	s_setprio 1
	v_mfma_f32_16x16x32_bf16 v[52:55], v[170:173], v[186:189], v[52:55]
	v_mfma_f32_16x16x32_bf16 v[48:51], v[178:181], v[186:189], v[48:51]
	v_mfma_f32_16x16x32_bf16 v[36:39], v[170:173], v[194:197], v[36:39]
	v_mfma_f32_16x16x32_bf16 v[32:35], v[178:181], v[194:197], v[32:35]
	v_mfma_f32_16x16x32_bf16 v[20:23], v[170:173], v[204:207], v[20:23]
	v_mfma_f32_16x16x32_bf16 v[16:19], v[178:181], v[204:207], v[16:19]
	v_mfma_f32_16x16x32_bf16 v[4:7], v[170:173], v[212:215], v[4:7]
	v_mfma_f32_16x16x32_bf16 v[0:3], v[178:181], v[212:215], v[0:3]
	v_mfma_f32_16x16x32_bf16 v[52:55], v[174:177], v[190:193], v[52:55]
	v_mfma_f32_16x16x32_bf16 v[48:51], v[182:185], v[190:193], v[48:51]
	v_mfma_f32_16x16x32_bf16 v[36:39], v[174:177], v[200:203], v[36:39]
	v_mfma_f32_16x16x32_bf16 v[32:35], v[182:185], v[200:203], v[32:35]
	v_mfma_f32_16x16x32_bf16 v[20:23], v[174:177], v[208:211], v[20:23]
	v_mfma_f32_16x16x32_bf16 v[16:19], v[182:185], v[208:211], v[16:19]
	v_mfma_f32_16x16x32_bf16 v[4:7], v[174:177], v[216:219], v[4:7]
	v_mfma_f32_16x16x32_bf16 v[0:3], v[182:185], v[216:219], v[0:3]
	s_setprio 0
	s_barrier
	ds_read_b128 v[144:147], v159
	ds_read_b128 v[148:151], v159 offset:1024
	ds_read_b128 v[162:165], v159 offset:2048
	ds_read_b128 v[166:169], v159 offset:3072
	ds_read_b128 v[170:173], v160
	ds_read_b128 v[174:177], v160 offset:1024
	ds_read_b128 v[178:181], v160 offset:2048
	ds_read_b128 v[182:185], v160 offset:3072
	s_add_u32 s30, s30, 0x40000
	s_addc_u32 s31, s31, 0
	s_mov_b32 m0, s43
	v_lshl_add_u64 v[226:227], s[30:31], 0, v[134:135]
	ds_read_b128 v[186:189], v158 offset:32768
	ds_read_b128 v[190:193], v158 offset:33792
	ds_read_b128 v[194:197], v158 offset:34816
	ds_read_b128 v[200:203], v158 offset:35840
	ds_read_b128 v[204:207], v158 offset:36864
	ds_read_b128 v[208:211], v158 offset:37888
	ds_read_b128 v[212:215], v158 offset:38912
	ds_read_b128 v[216:219], v158 offset:39936
	global_load_lds_dwordx4 v[226:227], off
	v_lshl_add_u64 v[226:227], s[30:31], 0, v[130:131]
	s_mov_b32 m0, s44
	s_nop 0
	global_load_lds_dwordx4 v[226:227], off
	s_waitcnt vmcnt(8)
	s_waitcnt lgkmcnt(0)
	s_barrier
	s_setprio 1
	s_waitcnt lgkmcnt(0)
	v_mfma_f32_16x16x32_bf16 v[124:127], v[144:147], v[186:189], v[124:127]
	v_mfma_f32_16x16x32_bf16 v[120:123], v[162:165], v[186:189], v[120:123]
	v_mfma_f32_16x16x32_bf16 v[108:111], v[144:147], v[194:197], v[108:111]
	v_mfma_f32_16x16x32_bf16 v[104:107], v[162:165], v[194:197], v[104:107]
	v_mfma_f32_16x16x32_bf16 v[92:95], v[144:147], v[204:207], v[92:95]
	v_mfma_f32_16x16x32_bf16 v[88:91], v[162:165], v[204:207], v[88:91]
	v_mfma_f32_16x16x32_bf16 v[76:79], v[144:147], v[212:215], v[76:79]
	v_mfma_f32_16x16x32_bf16 v[72:75], v[162:165], v[212:215], v[72:75]
	v_mfma_f32_16x16x32_bf16 v[124:127], v[148:151], v[190:193], v[124:127]
	v_mfma_f32_16x16x32_bf16 v[120:123], v[166:169], v[190:193], v[120:123]
	v_mfma_f32_16x16x32_bf16 v[108:111], v[148:151], v[200:203], v[108:111]
	v_mfma_f32_16x16x32_bf16 v[104:107], v[166:169], v[200:203], v[104:107]
	v_mfma_f32_16x16x32_bf16 v[92:95], v[148:151], v[208:211], v[92:95]
	v_mfma_f32_16x16x32_bf16 v[88:91], v[166:169], v[208:211], v[88:91]
	v_mfma_f32_16x16x32_bf16 v[76:79], v[148:151], v[216:219], v[76:79]
	v_mfma_f32_16x16x32_bf16 v[72:75], v[166:169], v[216:219], v[72:75]
	s_setprio 0
	s_setprio 1
	v_mfma_f32_16x16x32_bf16 v[116:119], v[170:173], v[186:189], v[116:119]
	v_mfma_f32_16x16x32_bf16 v[112:115], v[178:181], v[186:189], v[112:115]
	v_mfma_f32_16x16x32_bf16 v[100:103], v[170:173], v[194:197], v[100:103]
	v_mfma_f32_16x16x32_bf16 v[96:99], v[178:181], v[194:197], v[96:99]
	v_mfma_f32_16x16x32_bf16 v[84:87], v[170:173], v[204:207], v[84:87]
	v_mfma_f32_16x16x32_bf16 v[80:83], v[178:181], v[204:207], v[80:83]
	v_mfma_f32_16x16x32_bf16 v[68:71], v[170:173], v[212:215], v[68:71]
	v_mfma_f32_16x16x32_bf16 v[64:67], v[178:181], v[212:215], v[64:67]
	v_mfma_f32_16x16x32_bf16 v[116:119], v[174:177], v[190:193], v[116:119]
	v_mfma_f32_16x16x32_bf16 v[112:115], v[182:185], v[190:193], v[112:115]
	v_mfma_f32_16x16x32_bf16 v[100:103], v[174:177], v[200:203], v[100:103]
	v_mfma_f32_16x16x32_bf16 v[96:99], v[182:185], v[200:203], v[96:99]
	v_mfma_f32_16x16x32_bf16 v[84:87], v[174:177], v[208:211], v[84:87]
	v_mfma_f32_16x16x32_bf16 v[80:83], v[182:185], v[208:211], v[80:83]
	v_mfma_f32_16x16x32_bf16 v[68:71], v[174:177], v[216:219], v[68:71]
	v_mfma_f32_16x16x32_bf16 v[64:67], v[182:185], v[216:219], v[64:67]
	s_setprio 0
	s_barrier
; #define PG8_STAGE(bufoff, gbase, voff) do { _Pragma("unroll") for (int _i = 0; _i < 2; ++_i) \
;         __builtin_amdgcn_global_load_lds((const unsigned*)((const char*)(gbase) + (voff)[_i]), (PG8_LAS unsigned*)(lds + (bufoff) + ldsw + _i * 8192), 16, 0, 0); } while (0)
; #define PG8_LDA(dst, b, h) do { _Pragma("unroll") for (int m = 0; m < 4; ++m) _Pragma("unroll") for (int k = 0; k < 2; ++k) dst[m][k] = *(const PG8_LAS bf16x8*)(lds + PG8_SA(b, h) + aoff + m * 2048 + k * 1024); } while (0)
; #define PG8_MMA(ai, bj, At, Bt) do { __builtin_amdgcn_s_setprio(1); _Pragma("unroll") for (int m = 0; m < 4; ++m) _Pragma("unroll") for (int n = 0; n < 2; ++n) _Pragma("unroll") for (int k = 0; k < 2; ++k) \
;         acc[ai][bj][m][n] = __builtin_amdgcn_mfma_f32_16x16x32_bf16(Bt[n][k], At[m][k], acc[ai][bj][m][n], 0, 0, 0); __builtin_amdgcn_s_setprio(0); } while (0)
; #define PG8_WAIT_V(n) asm volatile("s_waitcnt vmcnt(" #n ")" ::: "memory")
; #define PG8_WAIT_L(n) asm volatile("s_waitcnt lgkmcnt(" #n ")" ::: "memory")
; #define PG8_BAR __builtin_amdgcn_s_barrier()
; #define PG8_SCHED __builtin_amdgcn_sched_barrier(0)
; __device__ __forceinline__ float ss_scale(const u64* ss, int row) { return __builtin_amdgcn_rsqf((float)ss[row] * (1.f / 4294967296.f / 1024.f) + EPS); }
; template <class Epi, class Sched, bool ALIGN_EPI = false, bool SP2 = false>
; __device__ __forceinline__ void gemm_phase(PG8_LAS unsigned char* lds, const Gemm g, const Sched& S, const Epi& E, const int tid) {
;     ...
;             PG8_LDA(At, 1, 1); PG8_STAGE(PG8_SB(1, 0), b3, voffB); PG8_STAGE(PG8_SB(1, 1), b3 + hstep, voffB); PG8_STAGE(PG8_SA(1, 0), a3, voffA);
;             PG8_WAIT_V(8); PG8_WAIT_L(0); PG8_BAR; PG8_MMA(1, 0, At, B0); PG8_MMA(1, 1, At, B1); PG8_BAR; PG8_SCHED;
;     __device__ __forceinline__ void operator()(const f32x4 (&acc)[2][2][4][2], const pg8::Unit& u, int wr, int wc, int fr, int fq) const {
;         const int row0 = u.pm * 256 + wr * 64 + fr, col0 = u.pn * 128 + wc * 32 + 8 * fq;
; #pragma unroll
;         for (int ai = 0; ai < 2; ++ai)
; #pragma unroll
;             for (int m = 0; m < 4; ++m) {
;                 const int row = row0 + ai * 128 + m * 16;
;                 float s = ss_scale(ss, row);
;                 if constexpr (NN) s *= __builtin_amdgcn_rsqf(s * s * (float)ssw[row] * (1.f / 4294967296.f / 1024.f) + EPS);
	s_mov_b32 m0, s47
	v_lshl_add_u64 v[152:153], v[152:153], 0, s[12:13]
	s_add_u32 s28, s28, 0x40080
	ds_read_b128 v[186:189], v158 offset:49152
	ds_read_b128 v[190:193], v158 offset:50176
	ds_read_b128 v[194:197], v158 offset:51200
	ds_read_b128 v[200:203], v158 offset:52224
	ds_read_b128 v[204:207], v158 offset:53248
	ds_read_b128 v[208:211], v158 offset:54272
	ds_read_b128 v[212:215], v158 offset:55296
	ds_read_b128 v[216:219], v158 offset:56320
	global_load_lds_dwordx4 v[152:153], off
	v_lshl_add_u64 v[152:153], v[220:221], 0, s[12:13]
	s_mov_b32 m0, s48
	s_addc_u32 s29, s29, 0
	global_load_lds_dwordx4 v[152:153], off
	v_lshl_add_u64 v[152:153], s[28:29], 0, v[132:133]
	s_mov_b32 m0, s51
	s_nop 0
	global_load_lds_dwordx4 v[152:153], off
	v_lshl_add_u64 v[152:153], s[28:29], 0, v[128:129]
	s_mov_b32 m0, s52
	s_nop 0
	global_load_lds_dwordx4 v[152:153], off
	v_lshl_add_u64 v[152:153], v[222:223], 0, s[12:13]
	s_mov_b32 m0, s49
	s_nop 0
	global_load_lds_dwordx4 v[152:153], off
	v_lshl_add_u64 v[152:153], v[224:225], 0, s[12:13]
	s_mov_b32 m0, s50
	s_nop 0
	global_load_lds_dwordx4 v[152:153], off
	s_waitcnt vmcnt(8)
	s_waitcnt lgkmcnt(0)
	s_barrier
	s_setprio 1
	s_waitcnt lgkmcnt(0)
	v_mfma_f32_16x16x32_bf16 v[60:63], v[144:147], v[186:189], v[60:63]
	v_mfma_f32_16x16x32_bf16 v[56:59], v[162:165], v[186:189], v[56:59]
	v_mfma_f32_16x16x32_bf16 v[44:47], v[144:147], v[194:197], v[44:47]
	v_mfma_f32_16x16x32_bf16 v[40:43], v[162:165], v[194:197], v[40:43]
	v_mfma_f32_16x16x32_bf16 v[28:31], v[144:147], v[204:207], v[28:31]
	v_mfma_f32_16x16x32_bf16 v[24:27], v[162:165], v[204:207], v[24:27]
	v_mfma_f32_16x16x32_bf16 v[12:15], v[144:147], v[212:215], v[12:15]
	v_mfma_f32_16x16x32_bf16 v[8:11], v[162:165], v[212:215], v[8:11]
	v_mfma_f32_16x16x32_bf16 v[60:63], v[148:151], v[190:193], v[60:63]
	v_mfma_f32_16x16x32_bf16 v[56:59], v[166:169], v[190:193], v[56:59]
	v_mfma_f32_16x16x32_bf16 v[44:47], v[148:151], v[200:203], v[44:47]
	v_mfma_f32_16x16x32_bf16 v[40:43], v[166:169], v[200:203], v[40:43]
	v_mfma_f32_16x16x32_bf16 v[28:31], v[148:151], v[208:211], v[28:31]
	v_mfma_f32_16x16x32_bf16 v[24:27], v[166:169], v[208:211], v[24:27]
	v_mfma_f32_16x16x32_bf16 v[12:15], v[148:151], v[216:219], v[12:15]
	v_mfma_f32_16x16x32_bf16 v[8:11], v[166:169], v[216:219], v[8:11]
	s_setprio 0
	s_setprio 1
	v_mfma_f32_16x16x32_bf16 v[52:55], v[170:173], v[186:189], v[52:55]
	v_mfma_f32_16x16x32_bf16 v[48:51], v[178:181], v[186:189], v[48:51]
	v_mfma_f32_16x16x32_bf16 v[36:39], v[170:173], v[194:197], v[36:39]
	v_mfma_f32_16x16x32_bf16 v[32:35], v[178:181], v[194:197], v[32:35]
	v_mfma_f32_16x16x32_bf16 v[20:23], v[170:173], v[204:207], v[20:23]
	v_mfma_f32_16x16x32_bf16 v[16:19], v[178:181], v[204:207], v[16:19]
	v_mfma_f32_16x16x32_bf16 v[4:7], v[170:173], v[212:215], v[4:7]
	v_mfma_f32_16x16x32_bf16 v[0:3], v[178:181], v[212:215], v[0:3]
	v_mfma_f32_16x16x32_bf16 v[52:55], v[174:177], v[190:193], v[52:55]
	v_mfma_f32_16x16x32_bf16 v[48:51], v[182:185], v[190:193], v[48:51]
	v_mfma_f32_16x16x32_bf16 v[36:39], v[174:177], v[200:203], v[36:39]
	v_mfma_f32_16x16x32_bf16 v[32:35], v[182:185], v[200:203], v[32:35]
	v_mfma_f32_16x16x32_bf16 v[20:23], v[174:177], v[208:211], v[20:23]
	v_mfma_f32_16x16x32_bf16 v[16:19], v[182:185], v[208:211], v[16:19]
	v_mfma_f32_16x16x32_bf16 v[4:7], v[174:177], v[216:219], v[4:7]
	v_mfma_f32_16x16x32_bf16 v[0:3], v[182:185], v[216:219], v[0:3]
	s_setprio 0
	s_barrier
	s_add_i32 s60, s60, 2
	s_add_u32 s26, s26, 0x100
	s_addc_u32 s27, s27, 0
	s_add_u32 s58, s58, 0x100
	s_addc_u32 s59, s59, 0
	s_cmp_gt_u32 s60, 13
	s_cbranch_scc0 .LBB0_1007
	v_lshl_add_u32 v144, s24, 8, v154
	v_mov_b32_e32 v145, 0
	v_lshl_add_u64 v[150:151], v[144:145], 3, s[8:9]
	global_load_dwordx2 v[176:177], v[150:151], off
	global_load_dwordx2 v[178:179], v[150:151], off offset:128
	global_load_dwordx2 v[180:181], v[150:151], off offset:256
	global_load_dwordx2 v[182:183], v[150:151], off offset:384
	global_load_dwordx2 v[184:185], v[150:151], off offset:1024
	global_load_dwordx2 v[186:187], v[150:151], off offset:1152
	global_load_dwordx2 v[188:189], v[150:151], off offset:1280
	global_load_dwordx2 v[190:191], v[150:151], off offset:1408
	v_lshl_add_u64 v[210:211], v[144:145], 3, s[10:11]
	global_load_dwordx2 v[192:193], v[210:211], off
	global_load_dwordx2 v[194:195], v[210:211], off offset:128
	global_load_dwordx2 v[196:197], v[210:211], off offset:256
	global_load_dwordx2 v[200:201], v[210:211], off offset:384
	global_load_dwordx2 v[202:203], v[210:211], off offset:1024
	global_load_dwordx2 v[204:205], v[210:211], off offset:1152
	global_load_dwordx2 v[206:207], v[210:211], off offset:1280
	global_load_dwordx2 v[208:209], v[210:211], off offset:1408
	v_lshl_or_b32 v148, s55, 7, v155
	v_mul_u32_u24_e32 v146, s54, v144
	v_lshl_add_u32 v146, v148, 1, v146
	v_mov_b32_e32 v147, 0
	v_lshl_add_u64 v[146:147], v[146:147], 0, s[6:7]
	v_mov_b32_e32 v164, 1.0
	v_mov_b32_e32 v165, 1.0
	s_mov_b32 s101, 0
	s_and_b64 vcc, exec, s[14:15]
	s_cbranch_vccz .LBB0_1010
	s_barrier
; __device__ __forceinline__ float ss_scale(const u64* ss, int row) { return __builtin_amdgcn_rsqf((float)ss[row] * (1.f / 4294967296.f / 1024.f) + EPS); }
; __device__ __forceinline__ unsigned pkbf(float lo, float hi) { typedef __bf16 bf2_t __attribute__((ext_vector_type(2))); f32x2 v = {lo, hi}; bf2_t b = __builtin_convertvector(v, bf2_t); return __builtin_bit_cast(unsigned, b); }
; __device__ __forceinline__ float silu_f(float g) { return g * __builtin_amdgcn_rcpf(1.f + __builtin_amdgcn_exp2f(-g * LOG2E)); }
;     __device__ __forceinline__ void operator()(const f32x4 (&acc)[2][2][4][2], const pg8::Unit& u, int wr, int wc, int fr, int fq) const {
;     ...
;             for (int m = 0; m < 4; ++m) {
;                 const int row = row0 + ai * 128 + m * 16;
;                 float s = ss_scale(ss, row);
;                 if constexpr (NN) s *= __builtin_amdgcn_rsqf(s * s * (float)ssw[row] * (1.f / 4294967296.f / 1024.f) + EPS);
;                 float a[8];
; #pragma unroll
;                 for (int n = 0; n < 2; ++n)
; #pragma unroll
;                     for (int i = 0; i < 4; ++i) { const float g = acc[ai][0][m][n][i] * s, uu = acc[ai][1][m][n][i] * s; a[4 * n + i] = silu_f(g) * uu; }
;                 u32x4 w; w.x = pkbf(a[0], a[1]); w.y = pkbf(a[2], a[3]); w.z = pkbf(a[4], a[5]); w.w = pkbf(a[6], a[7]);
;                 *(u32x4*)(O + (size_t)row * FF + col0) = w;
.LBB0_1010:
	s_andn2_b64 vcc, exec, s[2:3]
	s_mov_b64 s[2:3], -1
	s_waitcnt vmcnt(7)
	v_cvt_f32_u32_e32 v166, v177
	v_cvt_f32_u32_e32 v167, v176
	v_fmamk_f32 v166, v166, 0x4f800000, v167
	v_fmamk_f32 v166, v166, 0x2a800000, v161
	v_rsq_f32_e32 v166, v166
	v_cvt_f32_u32_e32 v167, v193
	v_cvt_f32_u32_e32 v152, v192
	v_fmamk_f32 v167, v167, 0x4f800000, v152
	v_mul_f32_e32 v152, v166, v166
	v_mul_f32_e32 v152, v152, v167
	v_fmamk_f32 v152, v152, 0x2a800000, v161
	v_rsq_f32_e32 v152, v152
	s_nop 0
	v_mul_f32_e32 v166, v166, v152
	v_mul_f32_e32 v152, 0xbfb8aa3b, v166
	v_mul_f32_e32 v162, v166, v166
	v_pk_mul_f32 v[168:169], v[124:125], v[152:153] op_sel_hi:[1,0]
	v_pk_mul_f32 v[170:171], v[126:127], v[152:153] op_sel_hi:[1,0]
	v_pk_mul_f32 v[172:173], v[120:121], v[152:153] op_sel_hi:[1,0]
	v_pk_mul_f32 v[174:175], v[122:123], v[152:153] op_sel_hi:[1,0]
	v_exp_f32_e32 v168, v168
	v_exp_f32_e32 v169, v169
	v_exp_f32_e32 v170, v170
	v_exp_f32_e32 v171, v171
	v_exp_f32_e32 v172, v172
	v_exp_f32_e32 v173, v173
	v_exp_f32_e32 v174, v174
	v_exp_f32_e32 v175, v175
	v_pk_add_f32 v[168:169], v[168:169], v[164:165]
	v_pk_add_f32 v[170:171], v[170:171], v[164:165]
	v_pk_add_f32 v[172:173], v[172:173], v[164:165]
	v_pk_add_f32 v[174:175], v[174:175], v[164:165]
	v_rcp_f32_e32 v168, v168
	v_rcp_f32_e32 v169, v169
	v_rcp_f32_e32 v170, v170
	v_rcp_f32_e32 v171, v171
	v_rcp_f32_e32 v172, v172
	v_rcp_f32_e32 v173, v173
	v_rcp_f32_e32 v174, v174
	v_rcp_f32_e32 v175, v175
	v_pk_mul_f32 v[124:125], v[124:125], v[116:117]
	v_pk_mul_f32 v[126:127], v[126:127], v[118:119]
	v_pk_mul_f32 v[120:121], v[120:121], v[112:113]
	v_pk_mul_f32 v[122:123], v[122:123], v[114:115]
	v_pk_mul_f32 v[124:125], v[124:125], v[168:169]
	v_pk_mul_f32 v[126:127], v[126:127], v[170:171]
	v_pk_mul_f32 v[120:121], v[120:121], v[172:173]
	v_pk_mul_f32 v[122:123], v[122:123], v[174:175]
	v_pk_mul_f32 v[124:125], v[124:125], v[162:163] op_sel_hi:[1,0]
	v_pk_mul_f32 v[126:127], v[126:127], v[162:163] op_sel_hi:[1,0]
	v_pk_mul_f32 v[120:121], v[120:121], v[162:163] op_sel_hi:[1,0]
	v_pk_mul_f32 v[122:123], v[122:123], v[162:163] op_sel_hi:[1,0]
	v_cvt_pk_bf16_f32 v116, v124, v125
	v_cvt_pk_bf16_f32 v117, v126, v127
	v_cvt_pk_bf16_f32 v118, v120, v121
	v_cvt_pk_bf16_f32 v119, v122, v123
	global_store_dwordx4 v[146:147], v[116:119], off
	s_waitcnt vmcnt(7)
	v_cvt_f32_u32_e32 v166, v179
	v_cvt_f32_u32_e32 v167, v178
	v_fmamk_f32 v166, v166, 0x4f800000, v167
	v_fmamk_f32 v166, v166, 0x2a800000, v161
	v_rsq_f32_e32 v166, v166
	v_cvt_f32_u32_e32 v167, v195
	v_cvt_f32_u32_e32 v152, v194
	v_fmamk_f32 v167, v167, 0x4f800000, v152
	v_mul_f32_e32 v152, v166, v166
	v_mul_f32_e32 v152, v152, v167
	v_fmamk_f32 v152, v152, 0x2a800000, v161
	v_rsq_f32_e32 v152, v152
	s_nop 0
	v_mul_f32_e32 v166, v166, v152
	v_mul_f32_e32 v152, 0xbfb8aa3b, v166
	v_mul_f32_e32 v162, v166, v166
	v_pk_mul_f32 v[168:169], v[108:109], v[152:153] op_sel_hi:[1,0]
	v_pk_mul_f32 v[170:171], v[110:111], v[152:153] op_sel_hi:[1,0]
	v_pk_mul_f32 v[172:173], v[104:105], v[152:153] op_sel_hi:[1,0]
	v_pk_mul_f32 v[174:175], v[106:107], v[152:153] op_sel_hi:[1,0]
	v_exp_f32_e32 v168, v168
	v_exp_f32_e32 v169, v169
	v_exp_f32_e32 v170, v170
	v_exp_f32_e32 v171, v171
	v_exp_f32_e32 v172, v172
	v_exp_f32_e32 v173, v173
	v_exp_f32_e32 v174, v174
	v_exp_f32_e32 v175, v175
	v_pk_add_f32 v[168:169], v[168:169], v[164:165]
	v_pk_add_f32 v[170:171], v[170:171], v[164:165]
	v_pk_add_f32 v[172:173], v[172:173], v[164:165]
	v_pk_add_f32 v[174:175], v[174:175], v[164:165]
	v_rcp_f32_e32 v168, v168
	v_rcp_f32_e32 v169, v169
	v_rcp_f32_e32 v170, v170
	v_rcp_f32_e32 v171, v171
	v_rcp_f32_e32 v172, v172
	v_rcp_f32_e32 v173, v173
	v_rcp_f32_e32 v174, v174
	v_rcp_f32_e32 v175, v175
	v_pk_mul_f32 v[108:109], v[108:109], v[100:101]
	v_pk_mul_f32 v[110:111], v[110:111], v[102:103]
	v_pk_mul_f32 v[104:105], v[104:105], v[96:97]
	v_pk_mul_f32 v[106:107], v[106:107], v[98:99]
	v_pk_mul_f32 v[108:109], v[108:109], v[168:169]
	v_pk_mul_f32 v[110:111], v[110:111], v[170:171]
	v_pk_mul_f32 v[104:105], v[104:105], v[172:173]
	v_pk_mul_f32 v[106:107], v[106:107], v[174:175]
	v_pk_mul_f32 v[108:109], v[108:109], v[162:163] op_sel_hi:[1,0]
	v_pk_mul_f32 v[110:111], v[110:111], v[162:163] op_sel_hi:[1,0]
	v_pk_mul_f32 v[104:105], v[104:105], v[162:163] op_sel_hi:[1,0]
	v_pk_mul_f32 v[106:107], v[106:107], v[162:163] op_sel_hi:[1,0]
	v_cvt_pk_bf16_f32 v100, v108, v109
	v_cvt_pk_bf16_f32 v101, v110, v111
	v_cvt_pk_bf16_f32 v102, v104, v105
	v_cvt_pk_bf16_f32 v103, v106, v107
	s_mov_b32 s100, 0x16000
	v_lshl_add_u64 v[148:149], v[146:147], 0, s[100:101]
	global_store_dwordx4 v[148:149], v[100:103], off
	s_waitcnt vmcnt(7)
; __device__ __forceinline__ float ss_scale(const u64* ss, int row) { return __builtin_amdgcn_rsqf((float)ss[row] * (1.f / 4294967296.f / 1024.f) + EPS); }
; __device__ __forceinline__ unsigned pkbf(float lo, float hi) { typedef __bf16 bf2_t __attribute__((ext_vector_type(2))); f32x2 v = {lo, hi}; bf2_t b = __builtin_convertvector(v, bf2_t); return __builtin_bit_cast(unsigned, b); }
; __device__ __forceinline__ float silu_f(float g) { return g * __builtin_amdgcn_rcpf(1.f + __builtin_amdgcn_exp2f(-g * LOG2E)); }
;     __device__ __forceinline__ void operator()(const f32x4 (&acc)[2][2][4][2], const pg8::Unit& u, int wr, int wc, int fr, int fq) const {
;     ...
;             for (int m = 0; m < 4; ++m) {
;                 const int row = row0 + ai * 128 + m * 16;
;                 float s = ss_scale(ss, row);
;                 if constexpr (NN) s *= __builtin_amdgcn_rsqf(s * s * (float)ssw[row] * (1.f / 4294967296.f / 1024.f) + EPS);
;                 float a[8];
; #pragma unroll
;                 for (int n = 0; n < 2; ++n)
; #pragma unroll
;                     for (int i = 0; i < 4; ++i) { const float g = acc[ai][0][m][n][i] * s, uu = acc[ai][1][m][n][i] * s; a[4 * n + i] = silu_f(g) * uu; }
;                 u32x4 w; w.x = pkbf(a[0], a[1]); w.y = pkbf(a[2], a[3]); w.z = pkbf(a[4], a[5]); w.w = pkbf(a[6], a[7]);
;                 *(u32x4*)(O + (size_t)row * FF + col0) = w;
	v_cvt_f32_u32_e32 v166, v181
	v_cvt_f32_u32_e32 v167, v180
	v_fmamk_f32 v166, v166, 0x4f800000, v167
	v_fmamk_f32 v166, v166, 0x2a800000, v161
	v_rsq_f32_e32 v166, v166
	v_cvt_f32_u32_e32 v167, v197
	v_cvt_f32_u32_e32 v152, v196
	v_fmamk_f32 v167, v167, 0x4f800000, v152
	v_mul_f32_e32 v152, v166, v166
	v_mul_f32_e32 v152, v152, v167
	v_fmamk_f32 v152, v152, 0x2a800000, v161
	v_rsq_f32_e32 v152, v152
	s_nop 0
	v_mul_f32_e32 v166, v166, v152
	v_mul_f32_e32 v152, 0xbfb8aa3b, v166
	v_mul_f32_e32 v162, v166, v166
	v_pk_mul_f32 v[168:169], v[92:93], v[152:153] op_sel_hi:[1,0]
	v_pk_mul_f32 v[170:171], v[94:95], v[152:153] op_sel_hi:[1,0]
	v_pk_mul_f32 v[172:173], v[88:89], v[152:153] op_sel_hi:[1,0]
	v_pk_mul_f32 v[174:175], v[90:91], v[152:153] op_sel_hi:[1,0]
	v_exp_f32_e32 v168, v168
	v_exp_f32_e32 v169, v169
	v_exp_f32_e32 v170, v170
	v_exp_f32_e32 v171, v171
	v_exp_f32_e32 v172, v172
	v_exp_f32_e32 v173, v173
	v_exp_f32_e32 v174, v174
	v_exp_f32_e32 v175, v175
	v_pk_add_f32 v[168:169], v[168:169], v[164:165]
	v_pk_add_f32 v[170:171], v[170:171], v[164:165]
	v_pk_add_f32 v[172:173], v[172:173], v[164:165]
	v_pk_add_f32 v[174:175], v[174:175], v[164:165]
	v_rcp_f32_e32 v168, v168
	v_rcp_f32_e32 v169, v169
	v_rcp_f32_e32 v170, v170
	v_rcp_f32_e32 v171, v171
	v_rcp_f32_e32 v172, v172
	v_rcp_f32_e32 v173, v173
	v_rcp_f32_e32 v174, v174
	v_rcp_f32_e32 v175, v175
	v_pk_mul_f32 v[92:93], v[92:93], v[84:85]
	v_pk_mul_f32 v[94:95], v[94:95], v[86:87]
	v_pk_mul_f32 v[88:89], v[88:89], v[80:81]
	v_pk_mul_f32 v[90:91], v[90:91], v[82:83]
	v_pk_mul_f32 v[92:93], v[92:93], v[168:169]
	v_pk_mul_f32 v[94:95], v[94:95], v[170:171]
	v_pk_mul_f32 v[88:89], v[88:89], v[172:173]
	v_pk_mul_f32 v[90:91], v[90:91], v[174:175]
	v_pk_mul_f32 v[92:93], v[92:93], v[162:163] op_sel_hi:[1,0]
	v_pk_mul_f32 v[94:95], v[94:95], v[162:163] op_sel_hi:[1,0]
	v_pk_mul_f32 v[88:89], v[88:89], v[162:163] op_sel_hi:[1,0]
	v_pk_mul_f32 v[90:91], v[90:91], v[162:163] op_sel_hi:[1,0]
	v_cvt_pk_bf16_f32 v84, v92, v93
	v_cvt_pk_bf16_f32 v85, v94, v95
	v_cvt_pk_bf16_f32 v86, v88, v89
	v_cvt_pk_bf16_f32 v87, v90, v91
	s_mov_b32 s100, 0x2c000
	v_lshl_add_u64 v[148:149], v[146:147], 0, s[100:101]
	global_store_dwordx4 v[148:149], v[84:87], off
	s_waitcnt vmcnt(7)
	v_cvt_f32_u32_e32 v166, v183
	v_cvt_f32_u32_e32 v167, v182
	v_fmamk_f32 v166, v166, 0x4f800000, v167
	v_fmamk_f32 v166, v166, 0x2a800000, v161
	v_rsq_f32_e32 v166, v166
	v_cvt_f32_u32_e32 v167, v201
	v_cvt_f32_u32_e32 v152, v200
	v_fmamk_f32 v167, v167, 0x4f800000, v152
	v_mul_f32_e32 v152, v166, v166
	v_mul_f32_e32 v152, v152, v167
	v_fmamk_f32 v152, v152, 0x2a800000, v161
	v_rsq_f32_e32 v152, v152
	s_nop 0
	v_mul_f32_e32 v166, v166, v152
	v_mul_f32_e32 v152, 0xbfb8aa3b, v166
	v_mul_f32_e32 v162, v166, v166
	v_pk_mul_f32 v[168:169], v[76:77], v[152:153] op_sel_hi:[1,0]
	v_pk_mul_f32 v[170:171], v[78:79], v[152:153] op_sel_hi:[1,0]
	v_pk_mul_f32 v[172:173], v[72:73], v[152:153] op_sel_hi:[1,0]
	v_pk_mul_f32 v[174:175], v[74:75], v[152:153] op_sel_hi:[1,0]
	v_exp_f32_e32 v168, v168
	v_exp_f32_e32 v169, v169
	v_exp_f32_e32 v170, v170
	v_exp_f32_e32 v171, v171
	v_exp_f32_e32 v172, v172
	v_exp_f32_e32 v173, v173
	v_exp_f32_e32 v174, v174
	v_exp_f32_e32 v175, v175
	v_pk_add_f32 v[168:169], v[168:169], v[164:165]
	v_pk_add_f32 v[170:171], v[170:171], v[164:165]
	v_pk_add_f32 v[172:173], v[172:173], v[164:165]
	v_pk_add_f32 v[174:175], v[174:175], v[164:165]
	v_rcp_f32_e32 v168, v168
	v_rcp_f32_e32 v169, v169
	v_rcp_f32_e32 v170, v170
	v_rcp_f32_e32 v171, v171
	v_rcp_f32_e32 v172, v172
	v_rcp_f32_e32 v173, v173
	v_rcp_f32_e32 v174, v174
	v_rcp_f32_e32 v175, v175
	v_pk_mul_f32 v[76:77], v[76:77], v[68:69]
	v_pk_mul_f32 v[78:79], v[78:79], v[70:71]
	v_pk_mul_f32 v[72:73], v[72:73], v[64:65]
	v_pk_mul_f32 v[74:75], v[74:75], v[66:67]
	v_pk_mul_f32 v[76:77], v[76:77], v[168:169]
	v_pk_mul_f32 v[78:79], v[78:79], v[170:171]
	v_pk_mul_f32 v[72:73], v[72:73], v[172:173]
	v_pk_mul_f32 v[74:75], v[74:75], v[174:175]
	v_pk_mul_f32 v[76:77], v[76:77], v[162:163] op_sel_hi:[1,0]
	v_pk_mul_f32 v[78:79], v[78:79], v[162:163] op_sel_hi:[1,0]
	v_pk_mul_f32 v[72:73], v[72:73], v[162:163] op_sel_hi:[1,0]
	v_pk_mul_f32 v[74:75], v[74:75], v[162:163] op_sel_hi:[1,0]
	v_cvt_pk_bf16_f32 v68, v76, v77
	v_cvt_pk_bf16_f32 v69, v78, v79
	v_cvt_pk_bf16_f32 v70, v72, v73
	v_cvt_pk_bf16_f32 v71, v74, v75
	s_mov_b32 s100, 0x42000
	v_lshl_add_u64 v[148:149], v[146:147], 0, s[100:101]
	global_store_dwordx4 v[148:149], v[68:71], off
	s_waitcnt vmcnt(7)
	v_cvt_f32_u32_e32 v166, v185
	v_cvt_f32_u32_e32 v167, v184
	v_fmamk_f32 v166, v166, 0x4f800000, v167
	v_fmamk_f32 v166, v166, 0x2a800000, v161
	v_rsq_f32_e32 v166, v166
	v_cvt_f32_u32_e32 v167, v203
	v_cvt_f32_u32_e32 v152, v202
	v_fmamk_f32 v167, v167, 0x4f800000, v152
	v_mul_f32_e32 v152, v166, v166
	v_mul_f32_e32 v152, v152, v167
	v_fmamk_f32 v152, v152, 0x2a800000, v161
	v_rsq_f32_e32 v152, v152
	s_nop 0
	v_mul_f32_e32 v166, v166, v152
	v_mul_f32_e32 v152, 0xbfb8aa3b, v166
	v_mul_f32_e32 v162, v166, v166
	v_pk_mul_f32 v[168:169], v[60:61], v[152:153] op_sel_hi:[1,0]
	v_pk_mul_f32 v[170:171], v[62:63], v[152:153] op_sel_hi:[1,0]
	v_pk_mul_f32 v[172:173], v[56:57], v[152:153] op_sel_hi:[1,0]
	v_pk_mul_f32 v[174:175], v[58:59], v[152:153] op_sel_hi:[1,0]
	v_exp_f32_e32 v168, v168
	v_exp_f32_e32 v169, v169
	v_exp_f32_e32 v170, v170
	v_exp_f32_e32 v171, v171
	v_exp_f32_e32 v172, v172
	v_exp_f32_e32 v173, v173
	v_exp_f32_e32 v174, v174
	v_exp_f32_e32 v175, v175
	v_pk_add_f32 v[168:169], v[168:169], v[164:165]
	v_pk_add_f32 v[170:171], v[170:171], v[164:165]
	v_pk_add_f32 v[172:173], v[172:173], v[164:165]
	v_pk_add_f32 v[174:175], v[174:175], v[164:165]
	v_rcp_f32_e32 v168, v168
	v_rcp_f32_e32 v169, v169
	v_rcp_f32_e32 v170, v170
	v_rcp_f32_e32 v171, v171
	v_rcp_f32_e32 v172, v172
	v_rcp_f32_e32 v173, v173
	v_rcp_f32_e32 v174, v174
	v_rcp_f32_e32 v175, v175
	v_pk_mul_f32 v[60:61], v[60:61], v[52:53]
	v_pk_mul_f32 v[62:63], v[62:63], v[54:55]
	v_pk_mul_f32 v[56:57], v[56:57], v[48:49]
	v_pk_mul_f32 v[58:59], v[58:59], v[50:51]
	v_pk_mul_f32 v[60:61], v[60:61], v[168:169]
	v_pk_mul_f32 v[62:63], v[62:63], v[170:171]
	v_pk_mul_f32 v[56:57], v[56:57], v[172:173]
	v_pk_mul_f32 v[58:59], v[58:59], v[174:175]
	v_pk_mul_f32 v[60:61], v[60:61], v[162:163] op_sel_hi:[1,0]
	v_pk_mul_f32 v[62:63], v[62:63], v[162:163] op_sel_hi:[1,0]
	v_pk_mul_f32 v[56:57], v[56:57], v[162:163] op_sel_hi:[1,0]
	v_pk_mul_f32 v[58:59], v[58:59], v[162:163] op_sel_hi:[1,0]
	v_cvt_pk_bf16_f32 v52, v60, v61
	v_cvt_pk_bf16_f32 v53, v62, v63
	v_cvt_pk_bf16_f32 v54, v56, v57
	v_cvt_pk_bf16_f32 v55, v58, v59
	s_mov_b32 s100, 0xb0000
	v_lshl_add_u64 v[148:149], v[146:147], 0, s[100:101]
	global_store_dwordx4 v[148:149], v[52:55], off
	s_waitcnt vmcnt(7)
; __device__ __forceinline__ float ss_scale(const u64* ss, int row) { return __builtin_amdgcn_rsqf((float)ss[row] * (1.f / 4294967296.f / 1024.f) + EPS); }
; __device__ __forceinline__ unsigned pkbf(float lo, float hi) { typedef __bf16 bf2_t __attribute__((ext_vector_type(2))); f32x2 v = {lo, hi}; bf2_t b = __builtin_convertvector(v, bf2_t); return __builtin_bit_cast(unsigned, b); }
; __device__ __forceinline__ float silu_f(float g) { return g * __builtin_amdgcn_rcpf(1.f + __builtin_amdgcn_exp2f(-g * LOG2E)); }
;     __device__ __forceinline__ void operator()(const f32x4 (&acc)[2][2][4][2], const pg8::Unit& u, int wr, int wc, int fr, int fq) const {
;     ...
;             for (int m = 0; m < 4; ++m) {
;                 const int row = row0 + ai * 128 + m * 16;
;                 float s = ss_scale(ss, row);
;                 if constexpr (NN) s *= __builtin_amdgcn_rsqf(s * s * (float)ssw[row] * (1.f / 4294967296.f / 1024.f) + EPS);
;                 float a[8];
; #pragma unroll
;                 for (int n = 0; n < 2; ++n)
; #pragma unroll
;                     for (int i = 0; i < 4; ++i) { const float g = acc[ai][0][m][n][i] * s, uu = acc[ai][1][m][n][i] * s; a[4 * n + i] = silu_f(g) * uu; }
;                 u32x4 w; w.x = pkbf(a[0], a[1]); w.y = pkbf(a[2], a[3]); w.z = pkbf(a[4], a[5]); w.w = pkbf(a[6], a[7]);
;                 *(u32x4*)(O + (size_t)row * FF + col0) = w;
	v_cvt_f32_u32_e32 v166, v187
	v_cvt_f32_u32_e32 v167, v186
	v_fmamk_f32 v166, v166, 0x4f800000, v167
	v_fmamk_f32 v166, v166, 0x2a800000, v161
	v_rsq_f32_e32 v166, v166
	v_cvt_f32_u32_e32 v167, v205
	v_cvt_f32_u32_e32 v152, v204
	v_fmamk_f32 v167, v167, 0x4f800000, v152
	v_mul_f32_e32 v152, v166, v166
	v_mul_f32_e32 v152, v152, v167
	v_fmamk_f32 v152, v152, 0x2a800000, v161
	v_rsq_f32_e32 v152, v152
	s_nop 0
	v_mul_f32_e32 v166, v166, v152
	v_mul_f32_e32 v152, 0xbfb8aa3b, v166
	v_mul_f32_e32 v162, v166, v166
	v_pk_mul_f32 v[168:169], v[44:45], v[152:153] op_sel_hi:[1,0]
	v_pk_mul_f32 v[170:171], v[46:47], v[152:153] op_sel_hi:[1,0]
	v_pk_mul_f32 v[172:173], v[40:41], v[152:153] op_sel_hi:[1,0]
	v_pk_mul_f32 v[174:175], v[42:43], v[152:153] op_sel_hi:[1,0]
	v_exp_f32_e32 v168, v168
	v_exp_f32_e32 v169, v169
	v_exp_f32_e32 v170, v170
	v_exp_f32_e32 v171, v171
	v_exp_f32_e32 v172, v172
	v_exp_f32_e32 v173, v173
	v_exp_f32_e32 v174, v174
	v_exp_f32_e32 v175, v175
	v_pk_add_f32 v[168:169], v[168:169], v[164:165]
	v_pk_add_f32 v[170:171], v[170:171], v[164:165]
	v_pk_add_f32 v[172:173], v[172:173], v[164:165]
	v_pk_add_f32 v[174:175], v[174:175], v[164:165]
	v_rcp_f32_e32 v168, v168
	v_rcp_f32_e32 v169, v169
	v_rcp_f32_e32 v170, v170
	v_rcp_f32_e32 v171, v171
	v_rcp_f32_e32 v172, v172
	v_rcp_f32_e32 v173, v173
	v_rcp_f32_e32 v174, v174
	v_rcp_f32_e32 v175, v175
	v_pk_mul_f32 v[44:45], v[44:45], v[36:37]
	v_pk_mul_f32 v[46:47], v[46:47], v[38:39]
	v_pk_mul_f32 v[40:41], v[40:41], v[32:33]
	v_pk_mul_f32 v[42:43], v[42:43], v[34:35]
	v_pk_mul_f32 v[44:45], v[44:45], v[168:169]
	v_pk_mul_f32 v[46:47], v[46:47], v[170:171]
	v_pk_mul_f32 v[40:41], v[40:41], v[172:173]
	v_pk_mul_f32 v[42:43], v[42:43], v[174:175]
	v_pk_mul_f32 v[44:45], v[44:45], v[162:163] op_sel_hi:[1,0]
	v_pk_mul_f32 v[46:47], v[46:47], v[162:163] op_sel_hi:[1,0]
	v_pk_mul_f32 v[40:41], v[40:41], v[162:163] op_sel_hi:[1,0]
	v_pk_mul_f32 v[42:43], v[42:43], v[162:163] op_sel_hi:[1,0]
	v_cvt_pk_bf16_f32 v36, v44, v45
	v_cvt_pk_bf16_f32 v37, v46, v47
	v_cvt_pk_bf16_f32 v38, v40, v41
	v_cvt_pk_bf16_f32 v39, v42, v43
	s_mov_b32 s100, 0xc6000
	v_lshl_add_u64 v[148:149], v[146:147], 0, s[100:101]
	global_store_dwordx4 v[148:149], v[36:39], off
	s_waitcnt vmcnt(7)
	v_cvt_f32_u32_e32 v166, v189
	v_cvt_f32_u32_e32 v167, v188
	v_fmamk_f32 v166, v166, 0x4f800000, v167
	v_fmamk_f32 v166, v166, 0x2a800000, v161
	v_rsq_f32_e32 v166, v166
	v_cvt_f32_u32_e32 v167, v207
	v_cvt_f32_u32_e32 v152, v206
	v_fmamk_f32 v167, v167, 0x4f800000, v152
	v_mul_f32_e32 v152, v166, v166
	v_mul_f32_e32 v152, v152, v167
	v_fmamk_f32 v152, v152, 0x2a800000, v161
	v_rsq_f32_e32 v152, v152
	s_nop 0
	v_mul_f32_e32 v166, v166, v152
	v_mul_f32_e32 v152, 0xbfb8aa3b, v166
	v_mul_f32_e32 v162, v166, v166
	v_pk_mul_f32 v[168:169], v[28:29], v[152:153] op_sel_hi:[1,0]
	v_pk_mul_f32 v[170:171], v[30:31], v[152:153] op_sel_hi:[1,0]
	v_pk_mul_f32 v[172:173], v[24:25], v[152:153] op_sel_hi:[1,0]
	v_pk_mul_f32 v[174:175], v[26:27], v[152:153] op_sel_hi:[1,0]
	v_exp_f32_e32 v168, v168
	v_exp_f32_e32 v169, v169
	v_exp_f32_e32 v170, v170
	v_exp_f32_e32 v171, v171
	v_exp_f32_e32 v172, v172
	v_exp_f32_e32 v173, v173
	v_exp_f32_e32 v174, v174
	v_exp_f32_e32 v175, v175
	v_pk_add_f32 v[168:169], v[168:169], v[164:165]
	v_pk_add_f32 v[170:171], v[170:171], v[164:165]
	v_pk_add_f32 v[172:173], v[172:173], v[164:165]
	v_pk_add_f32 v[174:175], v[174:175], v[164:165]
	v_rcp_f32_e32 v168, v168
	v_rcp_f32_e32 v169, v169
	v_rcp_f32_e32 v170, v170
	v_rcp_f32_e32 v171, v171
	v_rcp_f32_e32 v172, v172
	v_rcp_f32_e32 v173, v173
	v_rcp_f32_e32 v174, v174
	v_rcp_f32_e32 v175, v175
	v_pk_mul_f32 v[28:29], v[28:29], v[20:21]
	v_pk_mul_f32 v[30:31], v[30:31], v[22:23]
	v_pk_mul_f32 v[24:25], v[24:25], v[16:17]
	v_pk_mul_f32 v[26:27], v[26:27], v[18:19]
	v_pk_mul_f32 v[28:29], v[28:29], v[168:169]
	v_pk_mul_f32 v[30:31], v[30:31], v[170:171]
	v_pk_mul_f32 v[24:25], v[24:25], v[172:173]
	v_pk_mul_f32 v[26:27], v[26:27], v[174:175]
	v_pk_mul_f32 v[28:29], v[28:29], v[162:163] op_sel_hi:[1,0]
	v_pk_mul_f32 v[30:31], v[30:31], v[162:163] op_sel_hi:[1,0]
	v_pk_mul_f32 v[24:25], v[24:25], v[162:163] op_sel_hi:[1,0]
	v_pk_mul_f32 v[26:27], v[26:27], v[162:163] op_sel_hi:[1,0]
	v_cvt_pk_bf16_f32 v20, v28, v29
	v_cvt_pk_bf16_f32 v21, v30, v31
	v_cvt_pk_bf16_f32 v22, v24, v25
	v_cvt_pk_bf16_f32 v23, v26, v27
	s_mov_b32 s100, 0xdc000
	v_lshl_add_u64 v[148:149], v[146:147], 0, s[100:101]
	global_store_dwordx4 v[148:149], v[20:23], off
	s_waitcnt vmcnt(7)
	v_cvt_f32_u32_e32 v166, v191
	v_cvt_f32_u32_e32 v167, v190
	v_fmamk_f32 v166, v166, 0x4f800000, v167
	v_fmamk_f32 v166, v166, 0x2a800000, v161
	v_rsq_f32_e32 v166, v166
	v_cvt_f32_u32_e32 v167, v209
	v_cvt_f32_u32_e32 v152, v208
	v_fmamk_f32 v167, v167, 0x4f800000, v152
	v_mul_f32_e32 v152, v166, v166
	v_mul_f32_e32 v152, v152, v167
	v_fmamk_f32 v152, v152, 0x2a800000, v161
	v_rsq_f32_e32 v152, v152
	s_nop 0
	v_mul_f32_e32 v166, v166, v152
	v_mul_f32_e32 v152, 0xbfb8aa3b, v166
	v_mul_f32_e32 v162, v166, v166
	v_pk_mul_f32 v[168:169], v[12:13], v[152:153] op_sel_hi:[1,0]
	v_pk_mul_f32 v[170:171], v[14:15], v[152:153] op_sel_hi:[1,0]
	v_pk_mul_f32 v[172:173], v[8:9], v[152:153] op_sel_hi:[1,0]
	v_pk_mul_f32 v[174:175], v[10:11], v[152:153] op_sel_hi:[1,0]
	v_exp_f32_e32 v168, v168
	v_exp_f32_e32 v169, v169
	v_exp_f32_e32 v170, v170
	v_exp_f32_e32 v171, v171
	v_exp_f32_e32 v172, v172
	v_exp_f32_e32 v173, v173
	v_exp_f32_e32 v174, v174
	v_exp_f32_e32 v175, v175
	v_pk_add_f32 v[168:169], v[168:169], v[164:165]
	v_pk_add_f32 v[170:171], v[170:171], v[164:165]
	v_pk_add_f32 v[172:173], v[172:173], v[164:165]
	v_pk_add_f32 v[174:175], v[174:175], v[164:165]
	v_rcp_f32_e32 v168, v168
	v_rcp_f32_e32 v169, v169
	v_rcp_f32_e32 v170, v170
	v_rcp_f32_e32 v171, v171
	v_rcp_f32_e32 v172, v172
	v_rcp_f32_e32 v173, v173
	v_rcp_f32_e32 v174, v174
	v_rcp_f32_e32 v175, v175
	v_pk_mul_f32 v[12:13], v[12:13], v[4:5]
	v_pk_mul_f32 v[14:15], v[14:15], v[6:7]
	v_pk_mul_f32 v[8:9], v[8:9], v[0:1]
	v_pk_mul_f32 v[10:11], v[10:11], v[2:3]
	v_pk_mul_f32 v[12:13], v[12:13], v[168:169]
	v_pk_mul_f32 v[14:15], v[14:15], v[170:171]
	v_pk_mul_f32 v[8:9], v[8:9], v[172:173]
	v_pk_mul_f32 v[10:11], v[10:11], v[174:175]
	v_pk_mul_f32 v[12:13], v[12:13], v[162:163] op_sel_hi:[1,0]
	v_pk_mul_f32 v[14:15], v[14:15], v[162:163] op_sel_hi:[1,0]
	v_pk_mul_f32 v[8:9], v[8:9], v[162:163] op_sel_hi:[1,0]
	v_pk_mul_f32 v[10:11], v[10:11], v[162:163] op_sel_hi:[1,0]
	v_cvt_pk_bf16_f32 v4, v12, v13
	v_cvt_pk_bf16_f32 v5, v14, v15
	v_cvt_pk_bf16_f32 v6, v8, v9
	v_cvt_pk_bf16_f32 v7, v10, v11
	s_mov_b32 s100, 0xf2000
	v_lshl_add_u64 v[148:149], v[146:147], 0, s[100:101]
	global_store_dwordx4 v[148:149], v[4:7], off
	s_cbranch_vccnz .LBB0_1003
	s_andn2_b64 vcc, exec, s[4:5]
	s_cbranch_vccnz .LBB0_1002
	s_barrier
	s_branch .LBB0_1002
